# main GEMM K-loop without the s_setprio raise around the MFMA phases (on top of the pipelined conversion and SSD-B tail)
# speedup vs baseline: 1.0035x; 1.0035x over previous
.LBB0_1199:
	s_add_i32 s87, s86, 2
	s_add_u32 s30, s8, 0x80
	s_addc_u32 s31, s9, 0
	s_add_i32 s88, 16, 0x10000
	s_cmp_eq_u32 s57, s60
	s_cselect_b32 s31, s25, s31
	s_cselect_b32 s30, s24, s30
	v_add_u32_e32 v0, s88, v237
	s_cselect_b32 vcc_hi, s27, s85
	s_cselect_b32 vcc_lo, s26, s84
	s_add_i32 s89, 16, 0x14000
	ds_read_b128 v[132:135], v0
	ds_read_b128 v[136:139], v0 offset:1024
	ds_read_b128 v[152:155], v0 offset:2048
	ds_read_b128 v[156:159], v0 offset:3072
	v_add_u32_e32 v0, s89, v237
	ds_read_b128 v[160:163], v0
	ds_read_b128 v[164:167], v0 offset:1024
	ds_read_b128 v[168:171], v0 offset:2048
	ds_read_b128 v[172:175], v0 offset:3072
	v_lshl_add_u64 v[2:3], s[8:9], 0, v[150:151]
	s_add_i32 m0, s95, 0xc000
	ds_read_b128 v[176:179], v246
	ds_read_b128 v[180:183], v246 offset:1024
	ds_read_b128 v[184:187], v246 offset:2048
	ds_read_b128 v[188:191], v246 offset:3072
	ds_read_b128 v[192:195], v246 offset:4096
	ds_read_b128 v[196:199], v246 offset:5120
	ds_read_b128 v[200:203], v246 offset:6144
	ds_read_b128 v[204:207], v246 offset:7168
	global_load_lds_dwordx4 v[2:3], off
	v_lshl_add_u64 v[2:3], s[8:9], 0, v[148:149]
	s_add_i32 m0, s95, 0xe000
	s_nop 0
	global_load_lds_dwordx4 v[2:3], off
	s_waitcnt vmcnt(8)
	s_waitcnt lgkmcnt(0)
	s_barrier
	s_waitcnt lgkmcnt(0)
	v_mfma_f32_16x16x32_bf16 v[128:131], v[132:135], v[176:179], v[128:131]
	v_mfma_f32_16x16x32_bf16 v[124:127], v[152:155], v[176:179], v[124:127]
	v_mfma_f32_16x16x32_bf16 v[112:115], v[132:135], v[184:187], v[112:115]
	v_mfma_f32_16x16x32_bf16 v[108:111], v[152:155], v[184:187], v[108:111]
	v_mfma_f32_16x16x32_bf16 v[96:99], v[132:135], v[192:195], v[96:99]
	v_mfma_f32_16x16x32_bf16 v[92:95], v[152:155], v[192:195], v[92:95]
	v_mfma_f32_16x16x32_bf16 v[80:83], v[132:135], v[200:203], v[80:83]
	v_mfma_f32_16x16x32_bf16 v[76:79], v[152:155], v[200:203], v[76:79]
	v_mfma_f32_16x16x32_bf16 v[128:131], v[136:139], v[180:183], v[128:131]
	v_mfma_f32_16x16x32_bf16 v[124:127], v[156:159], v[180:183], v[124:127]
	v_mfma_f32_16x16x32_bf16 v[112:115], v[136:139], v[188:191], v[112:115]
	v_mfma_f32_16x16x32_bf16 v[108:111], v[156:159], v[188:191], v[108:111]
	v_mfma_f32_16x16x32_bf16 v[96:99], v[136:139], v[196:199], v[96:99]
	v_mfma_f32_16x16x32_bf16 v[92:95], v[156:159], v[196:199], v[92:95]
	v_mfma_f32_16x16x32_bf16 v[80:83], v[136:139], v[204:207], v[80:83]
	v_mfma_f32_16x16x32_bf16 v[76:79], v[156:159], v[204:207], v[76:79]
	v_mfma_f32_16x16x32_bf16 v[120:123], v[160:163], v[176:179], v[120:123]
	v_mfma_f32_16x16x32_bf16 v[116:119], v[168:171], v[176:179], v[116:119]
	v_mfma_f32_16x16x32_bf16 v[104:107], v[160:163], v[184:187], v[104:107]
	v_mfma_f32_16x16x32_bf16 v[100:103], v[168:171], v[184:187], v[100:103]
	v_mfma_f32_16x16x32_bf16 v[88:91], v[160:163], v[192:195], v[88:91]
	v_mfma_f32_16x16x32_bf16 v[84:87], v[168:171], v[192:195], v[84:87]
	v_mfma_f32_16x16x32_bf16 v[72:75], v[160:163], v[200:203], v[72:75]
	v_mfma_f32_16x16x32_bf16 v[68:71], v[168:171], v[200:203], v[68:71]
	v_mfma_f32_16x16x32_bf16 v[120:123], v[164:167], v[180:183], v[120:123]
	v_mfma_f32_16x16x32_bf16 v[116:119], v[172:175], v[180:183], v[116:119]
	v_mfma_f32_16x16x32_bf16 v[104:107], v[164:167], v[188:191], v[104:107]
	v_mfma_f32_16x16x32_bf16 v[100:103], v[172:175], v[188:191], v[100:103]
	v_mfma_f32_16x16x32_bf16 v[88:91], v[164:167], v[196:199], v[88:91]
	v_mfma_f32_16x16x32_bf16 v[84:87], v[172:175], v[196:199], v[84:87]
	v_mfma_f32_16x16x32_bf16 v[72:75], v[164:167], v[204:207], v[72:75]
	v_mfma_f32_16x16x32_bf16 v[68:71], v[172:175], v[204:207], v[68:71]
	s_barrier
	s_add_i32 s88, s88, s93
	v_lshl_add_u64 v[208:209], vcc, 0, v[142:143]
	s_mov_b32 m0, s88
	ds_read_b128 v[176:179], v246 offset:16384
	ds_read_b128 v[180:183], v246 offset:17408
	ds_read_b128 v[184:187], v246 offset:18432
	ds_read_b128 v[188:191], v246 offset:19456
	ds_read_b128 v[192:195], v246 offset:20480
	ds_read_b128 v[196:199], v246 offset:21504
	ds_read_b128 v[200:203], v246 offset:22528
	ds_read_b128 v[204:207], v246 offset:23552
	global_load_lds_dwordx4 v[208:209], off
	s_add_i32 m0, s88, 0x2000
	v_lshl_add_u64 v[210:211], vcc, 0, v[144:145]
	s_add_u32 vcc_lo, vcc_lo, s18
	s_addc_u32 vcc_hi, vcc_hi, 0
	s_add_i32 s88, s89, s93
	global_load_lds_dwordx4 v[210:211], off
	v_lshl_add_u64 v[212:213], vcc, 0, v[142:143]
	s_mov_b32 m0, s88
	v_lshl_add_u64 v[214:215], vcc, 0, v[144:145]
	global_load_lds_dwordx4 v[212:213], off
	s_add_i32 m0, s88, 0x2000
	v_lshl_add_u64 v[224:225], s[30:31], 0, v[142:143]
	global_load_lds_dwordx4 v[214:215], off
	s_mov_b32 m0, s95
	v_lshl_add_u64 v[226:227], s[30:31], 0, v[144:145]
	global_load_lds_dwordx4 v[224:225], off
	s_mov_b32 m0, s96
	s_nop 0
	global_load_lds_dwordx4 v[226:227], off
	s_waitcnt vmcnt(8)
	s_waitcnt lgkmcnt(0)
	s_barrier
	s_waitcnt lgkmcnt(0)
	v_mfma_f32_16x16x32_bf16 v[64:67], v[132:135], v[176:179], v[64:67]
	v_mfma_f32_16x16x32_bf16 v[60:63], v[152:155], v[176:179], v[60:63]
	v_mfma_f32_16x16x32_bf16 v[48:51], v[132:135], v[184:187], v[48:51]
	v_mfma_f32_16x16x32_bf16 v[44:47], v[152:155], v[184:187], v[44:47]
	v_mfma_f32_16x16x32_bf16 v[32:35], v[132:135], v[192:195], v[32:35]
	v_mfma_f32_16x16x32_bf16 v[28:31], v[152:155], v[192:195], v[28:31]
	v_mfma_f32_16x16x32_bf16 v[16:19], v[132:135], v[200:203], v[16:19]
	v_mfma_f32_16x16x32_bf16 v[12:15], v[152:155], v[200:203], v[12:15]
	v_mfma_f32_16x16x32_bf16 v[64:67], v[136:139], v[180:183], v[64:67]
	v_mfma_f32_16x16x32_bf16 v[60:63], v[156:159], v[180:183], v[60:63]
	v_mfma_f32_16x16x32_bf16 v[48:51], v[136:139], v[188:191], v[48:51]
	v_mfma_f32_16x16x32_bf16 v[44:47], v[156:159], v[188:191], v[44:47]
	v_mfma_f32_16x16x32_bf16 v[32:35], v[136:139], v[196:199], v[32:35]
	v_mfma_f32_16x16x32_bf16 v[28:31], v[156:159], v[196:199], v[28:31]
	v_mfma_f32_16x16x32_bf16 v[16:19], v[136:139], v[204:207], v[16:19]
	v_mfma_f32_16x16x32_bf16 v[12:15], v[156:159], v[204:207], v[12:15]
	v_mfma_f32_16x16x32_bf16 v[56:59], v[160:163], v[176:179], v[56:59]
	v_mfma_f32_16x16x32_bf16 v[52:55], v[168:171], v[176:179], v[52:55]
	v_mfma_f32_16x16x32_bf16 v[40:43], v[160:163], v[184:187], v[40:43]
	v_mfma_f32_16x16x32_bf16 v[36:39], v[168:171], v[184:187], v[36:39]
	v_mfma_f32_16x16x32_bf16 v[24:27], v[160:163], v[192:195], v[24:27]
	v_mfma_f32_16x16x32_bf16 v[20:23], v[168:171], v[192:195], v[20:23]
	v_mfma_f32_16x16x32_bf16 v[8:11], v[160:163], v[200:203], v[8:11]
	v_mfma_f32_16x16x32_bf16 v[2:5], v[168:171], v[200:203], v[4:7]
	v_mfma_f32_16x16x32_bf16 v[56:59], v[164:167], v[180:183], v[56:59]
	v_mfma_f32_16x16x32_bf16 v[52:55], v[172:175], v[180:183], v[52:55]
	v_mfma_f32_16x16x32_bf16 v[40:43], v[164:167], v[188:191], v[40:43]
	v_mfma_f32_16x16x32_bf16 v[36:39], v[172:175], v[188:191], v[36:39]
	v_mfma_f32_16x16x32_bf16 v[24:27], v[164:167], v[196:199], v[24:27]
	v_mfma_f32_16x16x32_bf16 v[20:23], v[172:175], v[196:199], v[20:23]
	v_mfma_f32_16x16x32_bf16 v[8:11], v[164:167], v[204:207], v[8:11]
	v_mfma_f32_16x16x32_bf16 v[2:5], v[172:175], v[204:207], v[2:5]
	s_barrier
	s_add_i32 s88, 16, 0x18000
	v_add_u32_e32 v0, s88, v237
	s_add_i32 s89, 16, 0x1c000
	ds_read_b128 v[132:135], v0
	ds_read_b128 v[136:139], v0 offset:1024
	ds_read_b128 v[152:155], v0 offset:2048
	ds_read_b128 v[156:159], v0 offset:3072
	v_add_u32_e32 v0, s89, v237
	ds_read_b128 v[160:163], v0
	ds_read_b128 v[164:167], v0 offset:1024
	ds_read_b128 v[168:171], v0 offset:2048
	ds_read_b128 v[172:175], v0 offset:3072
	s_add_u32 s30, s30, s18
	s_addc_u32 s31, s31, 0
	s_mov_b32 m0, s97
	v_lshl_add_u64 v[6:7], s[30:31], 0, v[142:143]
	ds_read_b128 v[176:179], v246 offset:32768
	ds_read_b128 v[180:183], v246 offset:33792
	ds_read_b128 v[184:187], v246 offset:34816
	ds_read_b128 v[188:191], v246 offset:35840
	ds_read_b128 v[192:195], v246 offset:36864
	ds_read_b128 v[196:199], v246 offset:37888
	ds_read_b128 v[200:203], v246 offset:38912
	ds_read_b128 v[204:207], v246 offset:39936
	global_load_lds_dwordx4 v[6:7], off
	v_lshl_add_u64 v[6:7], s[30:31], 0, v[144:145]
	s_mov_b32 m0, s58
	s_nop 0
	global_load_lds_dwordx4 v[6:7], off
	s_waitcnt vmcnt(8)
	s_waitcnt lgkmcnt(0)
	s_barrier
	s_waitcnt lgkmcnt(0)
	v_mfma_f32_16x16x32_bf16 v[128:131], v[132:135], v[176:179], v[128:131]
	v_mfma_f32_16x16x32_bf16 v[124:127], v[152:155], v[176:179], v[124:127]
	v_mfma_f32_16x16x32_bf16 v[112:115], v[132:135], v[184:187], v[112:115]
	v_mfma_f32_16x16x32_bf16 v[108:111], v[152:155], v[184:187], v[108:111]
	v_mfma_f32_16x16x32_bf16 v[96:99], v[132:135], v[192:195], v[96:99]
	v_mfma_f32_16x16x32_bf16 v[92:95], v[152:155], v[192:195], v[92:95]
	v_mfma_f32_16x16x32_bf16 v[80:83], v[132:135], v[200:203], v[80:83]
	v_mfma_f32_16x16x32_bf16 v[76:79], v[152:155], v[200:203], v[76:79]
	v_mfma_f32_16x16x32_bf16 v[128:131], v[136:139], v[180:183], v[128:131]
	v_mfma_f32_16x16x32_bf16 v[124:127], v[156:159], v[180:183], v[124:127]
	v_mfma_f32_16x16x32_bf16 v[112:115], v[136:139], v[188:191], v[112:115]
	v_mfma_f32_16x16x32_bf16 v[108:111], v[156:159], v[188:191], v[108:111]
	v_mfma_f32_16x16x32_bf16 v[96:99], v[136:139], v[196:199], v[96:99]
	v_mfma_f32_16x16x32_bf16 v[92:95], v[156:159], v[196:199], v[92:95]
	v_mfma_f32_16x16x32_bf16 v[80:83], v[136:139], v[204:207], v[80:83]
	v_mfma_f32_16x16x32_bf16 v[76:79], v[156:159], v[204:207], v[76:79]
	v_mfma_f32_16x16x32_bf16 v[120:123], v[160:163], v[176:179], v[120:123]
	v_mfma_f32_16x16x32_bf16 v[116:119], v[168:171], v[176:179], v[116:119]
	v_mfma_f32_16x16x32_bf16 v[104:107], v[160:163], v[184:187], v[104:107]
	v_mfma_f32_16x16x32_bf16 v[100:103], v[168:171], v[184:187], v[100:103]
	v_mfma_f32_16x16x32_bf16 v[88:91], v[160:163], v[192:195], v[88:91]
	v_mfma_f32_16x16x32_bf16 v[84:87], v[168:171], v[192:195], v[84:87]
	v_mfma_f32_16x16x32_bf16 v[72:75], v[160:163], v[200:203], v[72:75]
	v_mfma_f32_16x16x32_bf16 v[68:71], v[168:171], v[200:203], v[68:71]
	v_mfma_f32_16x16x32_bf16 v[120:123], v[164:167], v[180:183], v[120:123]
	v_mfma_f32_16x16x32_bf16 v[116:119], v[172:175], v[180:183], v[116:119]
	v_mfma_f32_16x16x32_bf16 v[104:107], v[164:167], v[188:191], v[104:107]
	v_mfma_f32_16x16x32_bf16 v[100:103], v[172:175], v[188:191], v[100:103]
	v_mfma_f32_16x16x32_bf16 v[88:91], v[164:167], v[196:199], v[88:91]
	v_mfma_f32_16x16x32_bf16 v[84:87], v[172:175], v[196:199], v[84:87]
	v_mfma_f32_16x16x32_bf16 v[72:75], v[164:167], v[204:207], v[72:75]
	v_mfma_f32_16x16x32_bf16 v[68:71], v[172:175], v[204:207], v[68:71]
	s_barrier
	s_add_i32 s30, s88, s93
	v_lshl_add_u64 v[6:7], v[208:209], 0, s[36:37]
	s_mov_b32 m0, s30
	ds_read_b128 v[176:179], v246 offset:49152
	ds_read_b128 v[180:183], v246 offset:50176
	ds_read_b128 v[184:187], v246 offset:51200
	ds_read_b128 v[188:191], v246 offset:52224
	ds_read_b128 v[192:195], v246 offset:53248
	ds_read_b128 v[196:199], v246 offset:54272
	ds_read_b128 v[200:203], v246 offset:55296
	ds_read_b128 v[204:207], v246 offset:56320
	global_load_lds_dwordx4 v[6:7], off
	v_lshl_add_u64 v[6:7], v[210:211], 0, s[36:37]
	s_add_i32 m0, s30, 0x2000
	s_add_i32 s30, s89, s93
	global_load_lds_dwordx4 v[6:7], off
	v_lshl_add_u64 v[6:7], v[212:213], 0, s[36:37]
	s_mov_b32 m0, s30
	s_nop 0
	global_load_lds_dwordx4 v[6:7], off
	v_lshl_add_u64 v[6:7], v[214:215], 0, s[36:37]
	s_add_i32 m0, s30, 0x2000
	s_nop 0
	global_load_lds_dwordx4 v[6:7], off
	v_lshl_add_u64 v[6:7], v[224:225], 0, s[36:37]
	s_mov_b32 m0, s21
	s_nop 0
	global_load_lds_dwordx4 v[6:7], off
	v_lshl_add_u64 v[6:7], v[226:227], 0, s[36:37]
	s_mov_b32 m0, s33
	s_nop 0
	global_load_lds_dwordx4 v[6:7], off
	s_waitcnt vmcnt(8)
	s_waitcnt lgkmcnt(0)
	s_barrier
	s_waitcnt lgkmcnt(0)
	v_mfma_f32_16x16x32_bf16 v[64:67], v[132:135], v[176:179], v[64:67]
	v_mfma_f32_16x16x32_bf16 v[60:63], v[152:155], v[176:179], v[60:63]
	v_mfma_f32_16x16x32_bf16 v[48:51], v[132:135], v[184:187], v[48:51]
	v_mfma_f32_16x16x32_bf16 v[44:47], v[152:155], v[184:187], v[44:47]
	v_mfma_f32_16x16x32_bf16 v[32:35], v[132:135], v[192:195], v[32:35]
	v_mfma_f32_16x16x32_bf16 v[28:31], v[152:155], v[192:195], v[28:31]
	v_mfma_f32_16x16x32_bf16 v[16:19], v[132:135], v[200:203], v[16:19]
	v_mfma_f32_16x16x32_bf16 v[12:15], v[152:155], v[200:203], v[12:15]
	v_mfma_f32_16x16x32_bf16 v[64:67], v[136:139], v[180:183], v[64:67]
	v_mfma_f32_16x16x32_bf16 v[60:63], v[156:159], v[180:183], v[60:63]
	v_mfma_f32_16x16x32_bf16 v[48:51], v[136:139], v[188:191], v[48:51]
	v_mfma_f32_16x16x32_bf16 v[44:47], v[156:159], v[188:191], v[44:47]
	v_mfma_f32_16x16x32_bf16 v[32:35], v[136:139], v[196:199], v[32:35]
	v_mfma_f32_16x16x32_bf16 v[28:31], v[156:159], v[196:199], v[28:31]
	v_mfma_f32_16x16x32_bf16 v[16:19], v[136:139], v[204:207], v[16:19]
	v_mfma_f32_16x16x32_bf16 v[12:15], v[156:159], v[204:207], v[12:15]
	v_mfma_f32_16x16x32_bf16 v[56:59], v[160:163], v[176:179], v[56:59]
	v_mfma_f32_16x16x32_bf16 v[52:55], v[168:171], v[176:179], v[52:55]
	v_mfma_f32_16x16x32_bf16 v[40:43], v[160:163], v[184:187], v[40:43]
	v_mfma_f32_16x16x32_bf16 v[36:39], v[168:171], v[184:187], v[36:39]
	v_mfma_f32_16x16x32_bf16 v[24:27], v[160:163], v[192:195], v[24:27]
	v_mfma_f32_16x16x32_bf16 v[20:23], v[168:171], v[192:195], v[20:23]
	v_mfma_f32_16x16x32_bf16 v[6:9], v[160:163], v[200:203], v[8:11]
	v_mfma_f32_16x16x32_bf16 v[2:5], v[168:171], v[200:203], v[2:5]
	v_mfma_f32_16x16x32_bf16 v[56:59], v[164:167], v[180:183], v[56:59]
	v_mfma_f32_16x16x32_bf16 v[52:55], v[172:175], v[180:183], v[52:55]
	v_mfma_f32_16x16x32_bf16 v[40:43], v[164:167], v[188:191], v[40:43]
	v_mfma_f32_16x16x32_bf16 v[36:39], v[172:175], v[188:191], v[36:39]
	v_mfma_f32_16x16x32_bf16 v[24:27], v[164:167], v[196:199], v[24:27]
	v_mfma_f32_16x16x32_bf16 v[20:23], v[172:175], v[196:199], v[20:23]
	v_mfma_f32_16x16x32_bf16 v[8:11], v[164:167], v[204:207], v[6:9]
	v_mfma_f32_16x16x32_bf16 v[4:7], v[172:175], v[204:207], v[2:5]
	s_barrier
	s_andn2_b64 vcc, exec, s[22:23]
	s_cbranch_vccnz .LBB0_1202
	s_bitcmp1_b32 s86, 1
	s_cselect_b64 s[30:31], -1, 0
	s_cmp_lt_u32 s87, s56
	s_cselect_b64 vcc, -1, 0
	s_and_b64 s[30:31], s[30:31], vcc
	s_andn2_b64 vcc, exec, s[30:31]
	s_cbranch_vccnz .LBB0_1202
	v_mov_b32_e32 v140, v234
	v_mov_b32_e32 v0, v235
	s_nop 0
	v_lshl_add_u32 v0, v0, 2, s4
	v_add_u32_e32 v2, s52, v0
	v_ashrrev_i32_e32 v3, 31, v2
	v_lshl_add_u64 v[136:137], v[2:3], 2, s[6:7]
	v_add_u32_e32 v174, s0, v140
	v_lshlrev_b64 v[2:3], 1, v[2:3]
	v_mad_i64_i32 v[152:153], s[30:31], v174, s2, v[2:3]
	s_add_u32 s30, s10, s60
	s_addc_u32 s31, s11, s61
	v_lshl_add_u64 v[152:153], s[30:31], 0, v[152:153]
	v_add_co_u32_e32 v154, vcc, s76, v152
	v_add_u32_e32 v175, 16, v174
	s_nop 0
	v_addc_co_u32_e32 v155, vcc, 0, v153, vcc
	v_add_co_u32_e32 v152, vcc, s77, v152
	global_load_dwordx4 v[132:135], v[136:137], off offset:-4096
	s_nop 0
	global_load_dwordx4 v[136:139], v[136:137], off
	v_addc_co_u32_e32 v153, vcc, 0, v153, vcc
	v_mad_i64_i32 v[156:157], vcc, v175, s2, v[2:3]
	v_lshl_add_u64 v[156:157], s[30:31], 0, v[156:157]
	v_add_co_u32_e32 v158, vcc, s76, v156
	v_add_u32_e32 v176, 32, v174
	s_nop 0
	v_addc_co_u32_e32 v159, vcc, 0, v157, vcc
	v_add_co_u32_e32 v156, vcc, s77, v156
	v_add_u32_e32 v177, 48, v174
	s_nop 0
	v_addc_co_u32_e32 v157, vcc, 0, v157, vcc
	global_load_dwordx2 v[182:183], v[154:155], off offset:3072
	global_load_dwordx2 v[184:185], v[152:153], off offset:1024
	global_load_dwordx2 v[186:187], v[158:159], off offset:3072
	global_load_dwordx2 v[188:189], v[156:157], off offset:1024
	v_mad_i64_i32 v[152:153], vcc, v176, s2, v[2:3]
	v_lshl_add_u64 v[152:153], s[30:31], 0, v[152:153]
	v_add_co_u32_e32 v154, vcc, s76, v152
	v_add_u32_e32 v178, 0x80, v174
	s_nop 0
	v_addc_co_u32_e32 v155, vcc, 0, v153, vcc
	v_add_co_u32_e32 v152, vcc, s77, v152
	v_add_u32_e32 v179, 0x90, v174
	s_nop 0
	v_addc_co_u32_e32 v153, vcc, 0, v153, vcc
	v_mad_i64_i32 v[156:157], vcc, v177, s2, v[2:3]
	v_lshl_add_u64 v[156:157], s[30:31], 0, v[156:157]
	v_add_co_u32_e32 v158, vcc, s76, v156
	v_add_u32_e32 v180, 0xa0, v174
	s_nop 0
	v_addc_co_u32_e32 v159, vcc, 0, v157, vcc
	v_add_co_u32_e32 v156, vcc, s77, v156
	v_add_u32_e32 v181, 0xb0, v174
	s_nop 0
	v_addc_co_u32_e32 v157, vcc, 0, v157, vcc
	global_load_dwordx2 v[170:171], v[154:155], off offset:3072
	global_load_dwordx2 v[172:173], v[152:153], off offset:1024
	global_load_dwordx2 v[166:167], v[158:159], off offset:3072
	global_load_dwordx2 v[168:169], v[156:157], off offset:1024
	v_mad_i64_i32 v[152:153], vcc, v178, s2, v[2:3]
	v_lshl_add_u64 v[152:153], s[30:31], 0, v[152:153]
	v_add_co_u32_e32 v154, vcc, s76, v152
	s_nop 1
	v_addc_co_u32_e32 v155, vcc, 0, v153, vcc
	v_add_co_u32_e32 v152, vcc, s77, v152
	s_nop 1
	v_addc_co_u32_e32 v153, vcc, 0, v153, vcc
	v_mad_i64_i32 v[156:157], vcc, v179, s2, v[2:3]
	v_lshl_add_u64 v[156:157], s[30:31], 0, v[156:157]
	v_add_co_u32_e32 v158, vcc, s76, v156
	s_nop 1
	v_addc_co_u32_e32 v159, vcc, 0, v157, vcc
	v_add_co_u32_e32 v156, vcc, s77, v156
	s_nop 1
	v_addc_co_u32_e32 v157, vcc, 0, v157, vcc
	global_load_dwordx2 v[162:163], v[154:155], off offset:3072
	global_load_dwordx2 v[164:165], v[152:153], off offset:1024
	s_nop 0
	global_load_dwordx2 v[158:159], v[158:159], off offset:3072
	s_nop 0
	global_load_dwordx2 v[160:161], v[156:157], off offset:1024
	v_mad_i64_i32 v[152:153], vcc, v180, s2, v[2:3]
	v_lshl_add_u64 v[152:153], s[30:31], 0, v[152:153]
	v_add_co_u32_e32 v154, vcc, s76, v152
	s_nop 1
	v_addc_co_u32_e32 v155, vcc, 0, v153, vcc
	v_add_co_u32_e32 v152, vcc, s77, v152
	s_nop 1
	v_addc_co_u32_e32 v153, vcc, 0, v153, vcc
	v_mad_i64_i32 v[2:3], vcc, v181, s2, v[2:3]
	v_lshl_add_u64 v[2:3], s[30:31], 0, v[2:3]
	v_add_co_u32_e32 v190, vcc, s76, v2
	s_nop 1
	v_addc_co_u32_e32 v191, vcc, 0, v3, vcc
	v_add_co_u32_e32 v192, vcc, s77, v2
	s_waitcnt vmcnt(0)
	v_lshlrev_b32_e32 v2, 16, v184
	v_add_f32_e32 v2, v136, v2
	v_mul_f32_e32 v2, 0xbfb8aa3b, v2
	v_exp_f32_e32 v140, v2
	v_lshlrev_b32_e32 v2, 16, v182
	v_add_f32_e32 v2, v132, v2
	v_mul_f32_e32 v2, 0xbfb8aa3b, v2
	v_exp_f32_e32 v141, v2
	v_addc_co_u32_e32 v193, vcc, 0, v3, vcc
	global_load_dwordx2 v[154:155], v[154:155], off offset:3072
	s_nop 0
	global_load_dwordx2 v[156:157], v[152:153], off offset:1024
	global_load_dwordx2 v[2:3], v[190:191], off offset:3072
	s_nop 0
	global_load_dwordx2 v[152:153], v[192:193], off offset:1024
	v_min_f32_e32 v190, 0x60ad78ec, v140
	v_min_f32_e32 v140, 0x60ad78ec, v141
	v_and_b32_e32 v141, 0xffff0000, v184
	v_add_f32_e32 v141, v137, v141
	v_mul_f32_e32 v141, 0xbfb8aa3b, v141
	v_exp_f32_e32 v141, v141
	v_and_b32_e32 v182, 0xffff0000, v182
	v_add_f32_e32 v182, v133, v182
	v_mul_f32_e32 v182, 0xbfb8aa3b, v182
	v_exp_f32_e32 v182, v182
	v_min_f32_e32 v191, 0x60ad78ec, v141
	v_lshlrev_b32_e32 v141, 16, v185
	v_add_f32_e32 v141, v138, v141
	v_add_f32_e32 v140, 1.0, v140
	v_mul_f32_e32 v141, 0xbfb8aa3b, v141
	v_rcp_f32_e32 v192, v140
	v_min_f32_e32 v140, 0x60ad78ec, v182
	v_exp_f32_e32 v141, v141
	v_lshlrev_b32_e32 v182, 16, v183
	v_add_f32_e32 v182, v134, v182
	v_mul_f32_e32 v182, 0xbfb8aa3b, v182
	v_and_b32_e32 v183, 0xffff0000, v183
	v_exp_f32_e32 v184, v182
	v_add_f32_e32 v183, v135, v183
	v_min_f32_e32 v182, 0x60ad78ec, v141
	v_and_b32_e32 v141, 0xffff0000, v185
	v_mul_f32_e32 v183, 0xbfb8aa3b, v183
	v_add_f32_e32 v141, v139, v141
	v_exp_f32_e32 v185, v183
	v_add_f32_e32 v140, 1.0, v140
	v_mul_f32_e32 v141, 0xbfb8aa3b, v141
	v_rcp_f32_e32 v193, v140
	v_min_f32_e32 v140, 0x60ad78ec, v184
	v_exp_f32_e32 v141, v141
	v_add_f32_e32 v140, 1.0, v140
	v_rcp_f32_e32 v184, v140
	v_min_f32_e32 v140, 0x60ad78ec, v185
	v_add_f32_e32 v140, 1.0, v140
	v_min_f32_e32 v183, 0x60ad78ec, v141
	v_rcp_f32_e32 v185, v140
	v_lshlrev_b32_e32 v140, 16, v188
	v_lshlrev_b32_e32 v141, 16, v186
	v_add_f32_e32 v140, v136, v140
	v_add_f32_e32 v141, v132, v141
	v_mul_f32_e32 v140, 0xbfb8aa3b, v140
	v_mul_f32_e32 v141, 0xbfb8aa3b, v141
	v_exp_f32_e32 v140, v140
	v_exp_f32_e32 v141, v141
	v_pk_add_f32 v[182:183], v[182:183], 1.0 op_sel_hi:[1,0]
	v_pk_add_f32 v[190:191], v[190:191], 1.0 op_sel_hi:[1,0]
	v_pk_mul_f32 v[182:183], v[182:183], v[184:185]
	v_pk_mul_f32 v[190:191], v[190:191], v[192:193]
	v_pk_mul_f32 v[130:131], v[130:131], v[182:183]
	v_min_f32_e32 v182, 0x60ad78ec, v140
	v_min_f32_e32 v140, 0x60ad78ec, v141
	v_and_b32_e32 v141, 0xffff0000, v188
	v_add_f32_e32 v141, v137, v141
	v_mul_f32_e32 v141, 0xbfb8aa3b, v141
	v_exp_f32_e32 v141, v141
	v_and_b32_e32 v183, 0xffff0000, v186
	v_add_f32_e32 v183, v133, v183
	v_mul_f32_e32 v183, 0xbfb8aa3b, v183
	v_exp_f32_e32 v185, v183
	v_min_f32_e32 v183, 0x60ad78ec, v141
	v_lshlrev_b32_e32 v141, 16, v189
	v_add_f32_e32 v141, v138, v141
	v_add_f32_e32 v140, 1.0, v140
	v_mul_f32_e32 v141, 0xbfb8aa3b, v141
	v_rcp_f32_e32 v184, v140
	v_min_f32_e32 v140, 0x60ad78ec, v185
	v_exp_f32_e32 v141, v141
	v_lshlrev_b32_e32 v185, 16, v187
	v_add_f32_e32 v185, v134, v185
	v_mul_f32_e32 v185, 0xbfb8aa3b, v185
	v_and_b32_e32 v187, 0xffff0000, v187
	v_exp_f32_e32 v188, v185
	v_add_f32_e32 v187, v135, v187
	v_min_f32_e32 v186, 0x60ad78ec, v141
	v_and_b32_e32 v141, 0xffff0000, v189
	v_mul_f32_e32 v187, 0xbfb8aa3b, v187
	v_add_f32_e32 v141, v139, v141
	v_exp_f32_e32 v189, v187
	v_add_f32_e32 v140, 1.0, v140
	v_mul_f32_e32 v141, 0xbfb8aa3b, v141
	v_rcp_f32_e32 v185, v140
	v_min_f32_e32 v140, 0x60ad78ec, v188
	v_exp_f32_e32 v141, v141
	v_add_f32_e32 v140, 1.0, v140
	v_rcp_f32_e32 v188, v140
	v_min_f32_e32 v140, 0x60ad78ec, v189
	v_add_f32_e32 v140, 1.0, v140
	v_min_f32_e32 v187, 0x60ad78ec, v141
	v_rcp_f32_e32 v189, v140
	v_lshlrev_b32_e32 v140, 16, v172
	v_lshlrev_b32_e32 v141, 16, v170
	v_add_f32_e32 v140, v136, v140
	v_add_f32_e32 v141, v132, v141
	v_mul_f32_e32 v140, 0xbfb8aa3b, v140
	v_mul_f32_e32 v141, 0xbfb8aa3b, v141
	v_exp_f32_e32 v140, v140
	v_exp_f32_e32 v141, v141
	v_pk_add_f32 v[182:183], v[182:183], 1.0 op_sel_hi:[1,0]
	v_and_b32_e32 v170, 0xffff0000, v170
	v_pk_mul_f32 v[182:183], v[182:183], v[184:185]
	v_add_f32_e32 v170, v133, v170
	v_pk_mul_f32 v[112:113], v[112:113], v[182:183]
	v_min_f32_e32 v182, 0x60ad78ec, v140
	v_min_f32_e32 v140, 0x60ad78ec, v141
	v_and_b32_e32 v141, 0xffff0000, v172
	v_add_f32_e32 v141, v137, v141
	v_mul_f32_e32 v141, 0xbfb8aa3b, v141
	v_exp_f32_e32 v141, v141
	v_mul_f32_e32 v170, 0xbfb8aa3b, v170
	v_exp_f32_e32 v170, v170
	v_pk_add_f32 v[186:187], v[186:187], 1.0 op_sel_hi:[1,0]
	v_min_f32_e32 v183, 0x60ad78ec, v141
	v_lshlrev_b32_e32 v141, 16, v173
	v_add_f32_e32 v141, v138, v141
	v_pk_mul_f32 v[184:185], v[186:187], v[188:189]
	v_add_f32_e32 v140, 1.0, v140
	v_mul_f32_e32 v141, 0xbfb8aa3b, v141
	v_pk_mul_f32 v[114:115], v[114:115], v[184:185]
	v_rcp_f32_e32 v184, v140
	v_min_f32_e32 v140, 0x60ad78ec, v170
	v_exp_f32_e32 v141, v141
	v_lshlrev_b32_e32 v170, 16, v171
	v_add_f32_e32 v170, v134, v170
	v_mul_f32_e32 v170, 0xbfb8aa3b, v170
	v_and_b32_e32 v171, 0xffff0000, v171
	v_exp_f32_e32 v172, v170
	v_add_f32_e32 v171, v135, v171
	v_min_f32_e32 v170, 0x60ad78ec, v141
	v_and_b32_e32 v141, 0xffff0000, v173
	v_mul_f32_e32 v171, 0xbfb8aa3b, v171
	v_add_f32_e32 v141, v139, v141
	v_exp_f32_e32 v173, v171
	v_add_f32_e32 v140, 1.0, v140
	v_mul_f32_e32 v141, 0xbfb8aa3b, v141
	v_rcp_f32_e32 v185, v140
	v_min_f32_e32 v140, 0x60ad78ec, v172
	v_exp_f32_e32 v141, v141
	v_add_f32_e32 v140, 1.0, v140
	v_rcp_f32_e32 v172, v140
	v_min_f32_e32 v140, 0x60ad78ec, v173
	v_add_f32_e32 v140, 1.0, v140
	v_min_f32_e32 v171, 0x60ad78ec, v141
	v_rcp_f32_e32 v173, v140
	v_lshlrev_b32_e32 v140, 16, v168
	v_lshlrev_b32_e32 v141, 16, v166
	v_add_f32_e32 v140, v136, v140
	v_add_f32_e32 v141, v132, v141
	v_mul_f32_e32 v140, 0xbfb8aa3b, v140
	v_mul_f32_e32 v141, 0xbfb8aa3b, v141
	v_exp_f32_e32 v140, v140
	v_exp_f32_e32 v141, v141
	v_pk_add_f32 v[170:171], v[170:171], 1.0 op_sel_hi:[1,0]
	v_and_b32_e32 v166, 0xffff0000, v166
	v_pk_mul_f32 v[170:171], v[170:171], v[172:173]
	v_add_f32_e32 v166, v133, v166
	v_pk_mul_f32 v[98:99], v[98:99], v[170:171]
	v_min_f32_e32 v170, 0x60ad78ec, v140
	v_min_f32_e32 v140, 0x60ad78ec, v141
	v_and_b32_e32 v141, 0xffff0000, v168
	v_add_f32_e32 v141, v137, v141
	v_mul_f32_e32 v141, 0xbfb8aa3b, v141
	v_exp_f32_e32 v141, v141
	v_mul_f32_e32 v166, 0xbfb8aa3b, v166
	v_exp_f32_e32 v166, v166
	v_add_f32_e32 v140, 1.0, v140
	v_min_f32_e32 v171, 0x60ad78ec, v141
	v_lshlrev_b32_e32 v141, 16, v169
	v_add_f32_e32 v141, v138, v141
	v_mul_f32_e32 v141, 0xbfb8aa3b, v141
	v_rcp_f32_e32 v172, v140
	v_min_f32_e32 v140, 0x60ad78ec, v166
	v_exp_f32_e32 v141, v141
	v_lshlrev_b32_e32 v166, 16, v167
	v_add_f32_e32 v166, v134, v166
	v_mul_f32_e32 v166, 0xbfb8aa3b, v166
	v_and_b32_e32 v167, 0xffff0000, v167
	v_exp_f32_e32 v168, v166
	v_add_f32_e32 v167, v135, v167
	v_min_f32_e32 v166, 0x60ad78ec, v141
	v_and_b32_e32 v141, 0xffff0000, v169
	v_mul_f32_e32 v167, 0xbfb8aa3b, v167
	v_add_f32_e32 v141, v139, v141
	v_exp_f32_e32 v169, v167
	v_add_f32_e32 v140, 1.0, v140
	v_mul_f32_e32 v141, 0xbfb8aa3b, v141
	v_rcp_f32_e32 v173, v140
	v_min_f32_e32 v140, 0x60ad78ec, v168
	v_exp_f32_e32 v141, v141
	v_add_f32_e32 v140, 1.0, v140
	v_rcp_f32_e32 v168, v140
	v_min_f32_e32 v140, 0x60ad78ec, v169
	v_add_f32_e32 v140, 1.0, v140
	v_min_f32_e32 v167, 0x60ad78ec, v141
	v_rcp_f32_e32 v169, v140
	v_lshlrev_b32_e32 v140, 16, v164
	v_lshlrev_b32_e32 v141, 16, v162
	v_add_f32_e32 v140, v136, v140
	v_add_f32_e32 v141, v132, v141
	v_mul_f32_e32 v140, 0xbfb8aa3b, v140
	v_mul_f32_e32 v141, 0xbfb8aa3b, v141
	v_exp_f32_e32 v140, v140
	v_exp_f32_e32 v141, v141
	v_pk_add_f32 v[166:167], v[166:167], 1.0 op_sel_hi:[1,0]
	v_and_b32_e32 v162, 0xffff0000, v162
	v_pk_mul_f32 v[166:167], v[166:167], v[168:169]
	v_add_f32_e32 v162, v133, v162
	v_pk_mul_f32 v[82:83], v[82:83], v[166:167]
	v_min_f32_e32 v166, 0x60ad78ec, v140
	v_min_f32_e32 v140, 0x60ad78ec, v141
	v_and_b32_e32 v141, 0xffff0000, v164
	v_add_f32_e32 v141, v137, v141
	v_mul_f32_e32 v141, 0xbfb8aa3b, v141
	v_exp_f32_e32 v141, v141
	v_mul_f32_e32 v162, 0xbfb8aa3b, v162
	v_exp_f32_e32 v162, v162
	v_add_f32_e32 v140, 1.0, v140
	v_min_f32_e32 v167, 0x60ad78ec, v141
	v_lshlrev_b32_e32 v141, 16, v165
	v_add_f32_e32 v141, v138, v141
	v_mul_f32_e32 v141, 0xbfb8aa3b, v141
	v_rcp_f32_e32 v168, v140
	v_min_f32_e32 v140, 0x60ad78ec, v162
	v_exp_f32_e32 v141, v141
	v_lshlrev_b32_e32 v162, 16, v163
	v_add_f32_e32 v162, v134, v162
	v_mul_f32_e32 v162, 0xbfb8aa3b, v162
	v_and_b32_e32 v163, 0xffff0000, v163
	v_exp_f32_e32 v164, v162
	v_add_f32_e32 v163, v135, v163
	v_min_f32_e32 v162, 0x60ad78ec, v141
	v_and_b32_e32 v141, 0xffff0000, v165
	v_mul_f32_e32 v163, 0xbfb8aa3b, v163
	v_add_f32_e32 v141, v139, v141
	v_exp_f32_e32 v165, v163
	v_add_f32_e32 v140, 1.0, v140
	v_mul_f32_e32 v141, 0xbfb8aa3b, v141
	v_rcp_f32_e32 v169, v140
	v_min_f32_e32 v140, 0x60ad78ec, v164
	v_exp_f32_e32 v141, v141
	v_add_f32_e32 v140, 1.0, v140
	v_rcp_f32_e32 v164, v140
	v_min_f32_e32 v140, 0x60ad78ec, v165
	v_add_f32_e32 v140, 1.0, v140
	v_min_f32_e32 v163, 0x60ad78ec, v141
	v_rcp_f32_e32 v165, v140
	v_lshlrev_b32_e32 v140, 16, v160
	v_lshlrev_b32_e32 v141, 16, v158
	v_add_f32_e32 v140, v136, v140
	v_add_f32_e32 v141, v132, v141
	v_mul_f32_e32 v140, 0xbfb8aa3b, v140
	v_mul_f32_e32 v141, 0xbfb8aa3b, v141
	v_exp_f32_e32 v140, v140
	v_exp_f32_e32 v141, v141
	v_pk_add_f32 v[162:163], v[162:163], 1.0 op_sel_hi:[1,0]
	v_and_b32_e32 v158, 0xffff0000, v158
	v_pk_mul_f32 v[162:163], v[162:163], v[164:165]
	v_add_f32_e32 v158, v133, v158
	v_pk_mul_f32 v[66:67], v[66:67], v[162:163]
	v_min_f32_e32 v162, 0x60ad78ec, v140
	v_min_f32_e32 v140, 0x60ad78ec, v141
	v_and_b32_e32 v141, 0xffff0000, v160
	v_add_f32_e32 v141, v137, v141
	v_mul_f32_e32 v141, 0xbfb8aa3b, v141
	v_exp_f32_e32 v141, v141
	v_mul_f32_e32 v158, 0xbfb8aa3b, v158
	v_exp_f32_e32 v158, v158
	v_add_f32_e32 v140, 1.0, v140
	v_min_f32_e32 v163, 0x60ad78ec, v141
	v_lshlrev_b32_e32 v141, 16, v161
	v_add_f32_e32 v141, v138, v141
	v_mul_f32_e32 v141, 0xbfb8aa3b, v141
	v_rcp_f32_e32 v164, v140
	v_min_f32_e32 v140, 0x60ad78ec, v158
	v_exp_f32_e32 v141, v141
	v_lshlrev_b32_e32 v158, 16, v159
	v_add_f32_e32 v158, v134, v158
	v_mul_f32_e32 v158, 0xbfb8aa3b, v158
	v_and_b32_e32 v159, 0xffff0000, v159
	v_exp_f32_e32 v160, v158
	v_add_f32_e32 v159, v135, v159
	v_min_f32_e32 v158, 0x60ad78ec, v141
	v_and_b32_e32 v141, 0xffff0000, v161
	v_mul_f32_e32 v159, 0xbfb8aa3b, v159
	v_add_f32_e32 v141, v139, v141
	v_exp_f32_e32 v161, v159
	v_add_f32_e32 v140, 1.0, v140
	v_mul_f32_e32 v141, 0xbfb8aa3b, v141
	v_rcp_f32_e32 v165, v140
	v_min_f32_e32 v140, 0x60ad78ec, v160
	v_exp_f32_e32 v141, v141
	v_add_f32_e32 v140, 1.0, v140
	v_rcp_f32_e32 v160, v140
	v_min_f32_e32 v140, 0x60ad78ec, v161
	v_add_f32_e32 v140, 1.0, v140
	v_min_f32_e32 v159, 0x60ad78ec, v141
	v_rcp_f32_e32 v161, v140
	s_waitcnt vmcnt(2)
	v_lshlrev_b32_e32 v140, 16, v156
	v_lshlrev_b32_e32 v141, 16, v154
	v_add_f32_e32 v140, v136, v140
	v_add_f32_e32 v141, v132, v141
	v_mul_f32_e32 v140, 0xbfb8aa3b, v140
	v_mul_f32_e32 v141, 0xbfb8aa3b, v141
	v_exp_f32_e32 v140, v140
	v_exp_f32_e32 v141, v141
	v_pk_add_f32 v[158:159], v[158:159], 1.0 op_sel_hi:[1,0]
	v_and_b32_e32 v154, 0xffff0000, v154
	v_pk_mul_f32 v[158:159], v[158:159], v[160:161]
	v_add_f32_e32 v154, v133, v154
	v_pk_mul_f32 v[50:51], v[50:51], v[158:159]
	v_min_f32_e32 v158, 0x60ad78ec, v140
	v_min_f32_e32 v140, 0x60ad78ec, v141
	v_and_b32_e32 v141, 0xffff0000, v156
	v_add_f32_e32 v141, v137, v141
	v_mul_f32_e32 v141, 0xbfb8aa3b, v141
	v_exp_f32_e32 v141, v141
	v_mul_f32_e32 v154, 0xbfb8aa3b, v154
	v_exp_f32_e32 v154, v154
	v_add_f32_e32 v140, 1.0, v140
	v_min_f32_e32 v159, 0x60ad78ec, v141
	v_lshlrev_b32_e32 v141, 16, v157
	v_add_f32_e32 v141, v138, v141
	v_rcp_f32_e32 v160, v140
	v_min_f32_e32 v140, 0x60ad78ec, v154
	v_mul_f32_e32 v141, 0xbfb8aa3b, v141
	v_lshlrev_b32_e32 v154, 16, v155
	v_exp_f32_e32 v141, v141
	v_add_f32_e32 v154, v134, v154
	v_mul_f32_e32 v154, 0xbfb8aa3b, v154
	v_and_b32_e32 v155, 0xffff0000, v155
	v_exp_f32_e32 v156, v154
	v_add_f32_e32 v155, v135, v155
	v_mul_f32_e32 v155, 0xbfb8aa3b, v155
	v_min_f32_e32 v154, 0x60ad78ec, v141
	v_and_b32_e32 v141, 0xffff0000, v157
	v_exp_f32_e32 v157, v155
	v_add_f32_e32 v140, 1.0, v140
	v_rcp_f32_e32 v161, v140
	v_min_f32_e32 v140, 0x60ad78ec, v156
	v_add_f32_e32 v140, 1.0, v140
	v_rcp_f32_e32 v156, v140
	v_min_f32_e32 v140, 0x60ad78ec, v157
	v_add_f32_e32 v140, 1.0, v140
	v_rcp_f32_e32 v157, v140
	s_waitcnt vmcnt(0)
	v_lshlrev_b32_e32 v140, 16, v152
	v_add_f32_e32 v136, v136, v140
	v_lshlrev_b32_e32 v140, 16, v2
	v_add_f32_e32 v132, v132, v140
	v_mul_f32_e32 v136, 0xbfb8aa3b, v136
	v_mul_f32_e32 v132, 0xbfb8aa3b, v132
	v_exp_f32_e32 v136, v136
	v_exp_f32_e32 v140, v132
	v_and_b32_e32 v2, 0xffff0000, v2
	v_add_f32_e32 v2, v133, v2
	v_min_f32_e32 v132, 0x60ad78ec, v136
	v_min_f32_e32 v136, 0x60ad78ec, v140
	v_and_b32_e32 v140, 0xffff0000, v152
	v_add_f32_e32 v137, v137, v140
	v_mul_f32_e32 v137, 0xbfb8aa3b, v137
	v_exp_f32_e32 v137, v137
	v_add_f32_e32 v133, 1.0, v136
	v_mul_f32_e32 v2, 0xbfb8aa3b, v2
	v_rcp_f32_e32 v136, v133
	v_min_f32_e32 v133, 0x60ad78ec, v137
	v_lshlrev_b32_e32 v137, 16, v153
	v_exp_f32_e32 v2, v2
	v_add_f32_e32 v137, v138, v137
	v_mul_f32_e32 v137, 0xbfb8aa3b, v137
	v_exp_f32_e32 v138, v137
	v_lshlrev_b32_e32 v137, 16, v3
	v_and_b32_e32 v3, 0xffff0000, v3
	v_add_f32_e32 v134, v134, v137
	v_add_f32_e32 v3, v135, v3
	v_min_f32_e32 v2, 0x60ad78ec, v2
	v_mul_f32_e32 v134, 0xbfb8aa3b, v134
	v_mul_f32_e32 v3, 0xbfb8aa3b, v3
	v_exp_f32_e32 v134, v134
	v_add_f32_e32 v2, 1.0, v2
	v_exp_f32_e32 v135, v3
	v_rcp_f32_e32 v137, v2
	v_min_f32_e32 v2, 0x60ad78ec, v138
	v_and_b32_e32 v138, 0xffff0000, v153
	v_add_f32_e32 v138, v139, v138
	v_mul_f32_e32 v138, 0xbfb8aa3b, v138
	v_min_f32_e32 v134, 0x60ad78ec, v134
	v_exp_f32_e32 v138, v138
	v_min_f32_e32 v135, 0x60ad78ec, v135
	v_add_f32_e32 v141, v139, v141
	v_add_f32_e32 v3, 1.0, v134
	v_add_f32_e32 v135, 1.0, v135
	v_mul_f32_e32 v141, 0xbfb8aa3b, v141
	v_rcp_f32_e32 v134, v3
	v_rcp_f32_e32 v135, v135
	v_exp_f32_e32 v141, v141
	v_min_f32_e32 v3, 0x60ad78ec, v138
	v_pk_add_f32 v[2:3], v[2:3], 1.0 op_sel_hi:[1,0]
	v_pk_add_f32 v[132:133], v[132:133], 1.0 op_sel_hi:[1,0]
	v_pk_mul_f32 v[2:3], v[2:3], v[134:135]
	v_min_f32_e32 v155, 0x60ad78ec, v141
	v_pk_mul_f32 v[18:19], v[18:19], v[2:3]
	v_add_u32_e32 v2, s20, v0
	v_pk_add_f32 v[154:155], v[154:155], 1.0 op_sel_hi:[1,0]
	v_ashrrev_i32_e32 v3, 31, v2
	v_pk_mul_f32 v[154:155], v[154:155], v[156:157]
	v_pk_mul_f32 v[152:153], v[132:133], v[136:137]
	v_lshl_add_u64 v[136:137], v[2:3], 2, s[6:7]
	v_lshlrev_b64 v[2:3], 1, v[2:3]
	v_pk_mul_f32 v[34:35], v[34:35], v[154:155]
	v_mad_i64_i32 v[154:155], vcc, v174, s2, v[2:3]
	v_lshl_add_u64 v[154:155], s[30:31], 0, v[154:155]
	v_add_co_u32_e32 v156, vcc, s76, v154
	v_pk_add_f32 v[182:183], v[182:183], 1.0 op_sel_hi:[1,0]
	s_nop 0
	v_addc_co_u32_e32 v157, vcc, 0, v155, vcc
	v_add_co_u32_e32 v154, vcc, s77, v154
	v_pk_mul_f32 v[182:183], v[182:183], v[184:185]
	s_nop 0
	v_addc_co_u32_e32 v155, vcc, 0, v155, vcc
	v_pk_mul_f32 v[96:97], v[96:97], v[182:183]
	v_pk_add_f32 v[158:159], v[158:159], 1.0 op_sel_hi:[1,0]
	global_load_dwordx4 v[132:135], v[136:137], off offset:-4096
	s_nop 0
	global_load_dwordx4 v[136:139], v[136:137], off
	v_pk_mul_f32 v[158:159], v[158:159], v[160:161]
	global_load_dwordx2 v[182:183], v[154:155], off offset:1024
	v_mad_i64_i32 v[154:155], vcc, v175, s2, v[2:3]
	v_lshl_add_u64 v[154:155], s[30:31], 0, v[154:155]
	v_pk_mul_f32 v[32:33], v[32:33], v[158:159]
	v_add_co_u32_e32 v158, vcc, s76, v154
	v_pk_mul_f32 v[16:17], v[16:17], v[152:153]
	s_nop 0
	v_addc_co_u32_e32 v159, vcc, 0, v155, vcc
	v_add_co_u32_e32 v154, vcc, s77, v154
	v_pk_add_f32 v[170:171], v[170:171], 1.0 op_sel_hi:[1,0]
	s_nop 0
	v_addc_co_u32_e32 v155, vcc, 0, v155, vcc
	global_load_dwordx2 v[184:185], v[158:159], off offset:3072
	global_load_dwordx2 v[186:187], v[154:155], off offset:1024
	global_load_dwordx2 v[188:189], v[156:157], off offset:3072
	v_mad_i64_i32 v[152:153], vcc, v176, s2, v[2:3]
	v_lshl_add_u64 v[152:153], s[30:31], 0, v[152:153]
	v_add_co_u32_e32 v154, vcc, s76, v152
	v_pk_add_f32 v[166:167], v[166:167], 1.0 op_sel_hi:[1,0]
	s_nop 0
	v_addc_co_u32_e32 v155, vcc, 0, v153, vcc
	v_add_co_u32_e32 v152, vcc, s77, v152
	v_pk_mul_f32 v[170:171], v[170:171], v[172:173]
	s_nop 0
	v_addc_co_u32_e32 v153, vcc, 0, v153, vcc
	v_mad_i64_i32 v[156:157], vcc, v177, s2, v[2:3]
	v_lshl_add_u64 v[156:157], s[30:31], 0, v[156:157]
	v_add_co_u32_e32 v158, vcc, s76, v156
	v_pk_mul_f32 v[166:167], v[166:167], v[168:169]
	s_nop 0
	v_addc_co_u32_e32 v159, vcc, 0, v157, vcc
	v_add_co_u32_e32 v156, vcc, s77, v156
	v_pk_mul_f32 v[80:81], v[80:81], v[170:171]
	v_pk_mul_f32 v[64:65], v[64:65], v[166:167]
	v_addc_co_u32_e32 v157, vcc, 0, v157, vcc
	global_load_dwordx2 v[170:171], v[154:155], off offset:3072
	global_load_dwordx2 v[172:173], v[152:153], off offset:1024
	global_load_dwordx2 v[166:167], v[158:159], off offset:3072
	global_load_dwordx2 v[168:169], v[156:157], off offset:1024
	v_mad_i64_i32 v[152:153], vcc, v178, s2, v[2:3]
	v_lshl_add_u64 v[152:153], s[30:31], 0, v[152:153]
	v_add_co_u32_e32 v154, vcc, s76, v152
	v_pk_add_f32 v[162:163], v[162:163], 1.0 op_sel_hi:[1,0]
	s_nop 0
	v_addc_co_u32_e32 v155, vcc, 0, v153, vcc
	v_add_co_u32_e32 v152, vcc, s77, v152
	v_pk_mul_f32 v[162:163], v[162:163], v[164:165]
	s_nop 0
	v_addc_co_u32_e32 v153, vcc, 0, v153, vcc
	v_mad_i64_i32 v[156:157], vcc, v179, s2, v[2:3]
	v_lshl_add_u64 v[156:157], s[30:31], 0, v[156:157]
	v_add_co_u32_e32 v158, vcc, s76, v156
	v_pk_mul_f32 v[48:49], v[48:49], v[162:163]
	s_nop 0
	v_addc_co_u32_e32 v159, vcc, 0, v157, vcc
	v_add_co_u32_e32 v156, vcc, s77, v156
	v_pk_mul_f32 v[128:129], v[128:129], v[190:191]
	s_nop 0
	v_addc_co_u32_e32 v157, vcc, 0, v157, vcc
	global_load_dwordx2 v[162:163], v[154:155], off offset:3072
	global_load_dwordx2 v[164:165], v[152:153], off offset:1024
	s_nop 0
	global_load_dwordx2 v[158:159], v[158:159], off offset:3072
	s_nop 0
	global_load_dwordx2 v[160:161], v[156:157], off offset:1024
	v_mad_i64_i32 v[152:153], vcc, v180, s2, v[2:3]
	v_lshl_add_u64 v[152:153], s[30:31], 0, v[152:153]
	v_add_co_u32_e32 v154, vcc, s76, v152
	s_nop 1
	v_addc_co_u32_e32 v155, vcc, 0, v153, vcc
	v_add_co_u32_e32 v152, vcc, s77, v152
	s_nop 1
	v_addc_co_u32_e32 v153, vcc, 0, v153, vcc
	v_mad_i64_i32 v[2:3], vcc, v181, s2, v[2:3]
	v_lshl_add_u64 v[2:3], s[30:31], 0, v[2:3]
	v_add_co_u32_e32 v190, vcc, s76, v2
	s_nop 1
	v_addc_co_u32_e32 v191, vcc, 0, v3, vcc
	v_add_co_u32_e32 v192, vcc, s77, v2
	s_waitcnt vmcnt(11)
	v_lshlrev_b32_e32 v2, 16, v182
	v_add_f32_e32 v2, v136, v2
	v_mul_f32_e32 v2, 0xbfb8aa3b, v2
	v_exp_f32_e32 v140, v2
	s_waitcnt vmcnt(8)
	v_lshlrev_b32_e32 v2, 16, v188
	v_add_f32_e32 v2, v132, v2
	v_mul_f32_e32 v2, 0xbfb8aa3b, v2
	v_exp_f32_e32 v141, v2
	v_addc_co_u32_e32 v193, vcc, 0, v3, vcc
	global_load_dwordx2 v[154:155], v[154:155], off offset:3072
	s_nop 0
	global_load_dwordx2 v[156:157], v[152:153], off offset:1024
	global_load_dwordx2 v[2:3], v[190:191], off offset:3072
	s_nop 0
	global_load_dwordx2 v[152:153], v[192:193], off offset:1024
	v_min_f32_e32 v190, 0x60ad78ec, v140
	v_min_f32_e32 v140, 0x60ad78ec, v141
	v_and_b32_e32 v141, 0xffff0000, v182
	v_add_f32_e32 v141, v137, v141
	v_mul_f32_e32 v141, 0xbfb8aa3b, v141
	v_exp_f32_e32 v141, v141
	v_and_b32_e32 v182, 0xffff0000, v188
	v_add_f32_e32 v182, v133, v182
	v_mul_f32_e32 v182, 0xbfb8aa3b, v182
	v_exp_f32_e32 v182, v182
	v_min_f32_e32 v191, 0x60ad78ec, v141
	v_lshlrev_b32_e32 v141, 16, v183
	v_add_f32_e32 v141, v138, v141
	v_mul_f32_e32 v141, 0xbfb8aa3b, v141
	v_add_f32_e32 v140, 1.0, v140
	v_exp_f32_e32 v141, v141
	v_rcp_f32_e32 v192, v140
	v_min_f32_e32 v140, 0x60ad78ec, v182
	v_lshlrev_b32_e32 v182, 16, v189
	v_add_f32_e32 v182, v134, v182
	v_mul_f32_e32 v182, 0xbfb8aa3b, v182
	v_exp_f32_e32 v188, v182
	v_min_f32_e32 v182, 0x60ad78ec, v141
	v_and_b32_e32 v141, 0xffff0000, v183
	v_and_b32_e32 v183, 0xffff0000, v189
	v_add_f32_e32 v183, v135, v183
	v_mul_f32_e32 v183, 0xbfb8aa3b, v183
	v_add_f32_e32 v141, v139, v141
	v_exp_f32_e32 v189, v183
	v_add_f32_e32 v140, 1.0, v140
	v_mul_f32_e32 v141, 0xbfb8aa3b, v141
	v_rcp_f32_e32 v193, v140
	v_min_f32_e32 v140, 0x60ad78ec, v188
	v_exp_f32_e32 v141, v141
	v_add_f32_e32 v140, 1.0, v140
	v_rcp_f32_e32 v188, v140
	v_min_f32_e32 v140, 0x60ad78ec, v189
	v_add_f32_e32 v140, 1.0, v140
	v_min_f32_e32 v183, 0x60ad78ec, v141
	v_rcp_f32_e32 v189, v140
	v_lshlrev_b32_e32 v140, 16, v186
	v_lshlrev_b32_e32 v141, 16, v184
	v_add_f32_e32 v140, v136, v140
	v_add_f32_e32 v141, v132, v141
	v_mul_f32_e32 v140, 0xbfb8aa3b, v140
	v_mul_f32_e32 v141, 0xbfb8aa3b, v141
	v_exp_f32_e32 v140, v140
	v_exp_f32_e32 v141, v141
	v_pk_add_f32 v[182:183], v[182:183], 1.0 op_sel_hi:[1,0]
	v_pk_add_f32 v[190:191], v[190:191], 1.0 op_sel_hi:[1,0]
	v_pk_mul_f32 v[182:183], v[182:183], v[188:189]
	v_pk_mul_f32 v[190:191], v[190:191], v[192:193]
	v_pk_mul_f32 v[126:127], v[126:127], v[182:183]
	v_min_f32_e32 v182, 0x60ad78ec, v140
	v_min_f32_e32 v140, 0x60ad78ec, v141
	v_and_b32_e32 v141, 0xffff0000, v186
	v_add_f32_e32 v141, v137, v141
	v_mul_f32_e32 v141, 0xbfb8aa3b, v141
	v_exp_f32_e32 v141, v141
	v_and_b32_e32 v183, 0xffff0000, v184
	v_add_f32_e32 v183, v133, v183
	v_mul_f32_e32 v183, 0xbfb8aa3b, v183
	v_exp_f32_e32 v184, v183
	v_min_f32_e32 v183, 0x60ad78ec, v141
	v_lshlrev_b32_e32 v141, 16, v187
	v_add_f32_e32 v141, v138, v141
	v_add_f32_e32 v140, 1.0, v140
	v_mul_f32_e32 v141, 0xbfb8aa3b, v141
	v_rcp_f32_e32 v188, v140
	v_min_f32_e32 v140, 0x60ad78ec, v184
	v_exp_f32_e32 v141, v141
	v_lshlrev_b32_e32 v184, 16, v185
	v_add_f32_e32 v184, v134, v184
	v_mul_f32_e32 v184, 0xbfb8aa3b, v184
	v_and_b32_e32 v185, 0xffff0000, v185
	v_exp_f32_e32 v186, v184
	v_add_f32_e32 v185, v135, v185
	v_min_f32_e32 v184, 0x60ad78ec, v141
	v_and_b32_e32 v141, 0xffff0000, v187
	v_mul_f32_e32 v185, 0xbfb8aa3b, v185
	v_add_f32_e32 v141, v139, v141
	v_exp_f32_e32 v187, v185
	v_add_f32_e32 v140, 1.0, v140
	v_mul_f32_e32 v141, 0xbfb8aa3b, v141
	v_rcp_f32_e32 v189, v140
	v_min_f32_e32 v140, 0x60ad78ec, v186
	v_exp_f32_e32 v141, v141
	v_add_f32_e32 v140, 1.0, v140
	v_rcp_f32_e32 v186, v140
	v_min_f32_e32 v140, 0x60ad78ec, v187
	v_add_f32_e32 v140, 1.0, v140
	v_min_f32_e32 v185, 0x60ad78ec, v141
	v_rcp_f32_e32 v187, v140
	s_waitcnt vmcnt(10)
	v_lshlrev_b32_e32 v140, 16, v172
	v_lshlrev_b32_e32 v141, 16, v170
	v_add_f32_e32 v140, v136, v140
	v_add_f32_e32 v141, v132, v141
	v_mul_f32_e32 v140, 0xbfb8aa3b, v140
	v_mul_f32_e32 v141, 0xbfb8aa3b, v141
	v_exp_f32_e32 v140, v140
	v_exp_f32_e32 v141, v141
	v_pk_add_f32 v[182:183], v[182:183], 1.0 op_sel_hi:[1,0]
	v_and_b32_e32 v170, 0xffff0000, v170
	v_pk_mul_f32 v[182:183], v[182:183], v[188:189]
	v_add_f32_e32 v170, v133, v170
	v_pk_mul_f32 v[108:109], v[108:109], v[182:183]
	v_min_f32_e32 v182, 0x60ad78ec, v140
	v_min_f32_e32 v140, 0x60ad78ec, v141
	v_and_b32_e32 v141, 0xffff0000, v172
	v_add_f32_e32 v141, v137, v141
	v_mul_f32_e32 v141, 0xbfb8aa3b, v141
	v_exp_f32_e32 v141, v141
	v_mul_f32_e32 v170, 0xbfb8aa3b, v170
	v_exp_f32_e32 v170, v170
	v_pk_add_f32 v[184:185], v[184:185], 1.0 op_sel_hi:[1,0]
	v_min_f32_e32 v183, 0x60ad78ec, v141
	v_lshlrev_b32_e32 v141, 16, v173
	v_add_f32_e32 v141, v138, v141
	v_pk_mul_f32 v[184:185], v[184:185], v[186:187]
	v_add_f32_e32 v140, 1.0, v140
	v_mul_f32_e32 v141, 0xbfb8aa3b, v141
	v_pk_mul_f32 v[110:111], v[110:111], v[184:185]
	v_rcp_f32_e32 v184, v140
	v_min_f32_e32 v140, 0x60ad78ec, v170
	v_exp_f32_e32 v141, v141
	v_lshlrev_b32_e32 v170, 16, v171
	v_add_f32_e32 v170, v134, v170
	v_mul_f32_e32 v170, 0xbfb8aa3b, v170
	v_and_b32_e32 v171, 0xffff0000, v171
	v_exp_f32_e32 v172, v170
	v_add_f32_e32 v171, v135, v171
	v_min_f32_e32 v170, 0x60ad78ec, v141
	v_and_b32_e32 v141, 0xffff0000, v173
	v_mul_f32_e32 v171, 0xbfb8aa3b, v171
	v_add_f32_e32 v141, v139, v141
	v_exp_f32_e32 v173, v171
	v_add_f32_e32 v140, 1.0, v140
	v_mul_f32_e32 v141, 0xbfb8aa3b, v141
	v_rcp_f32_e32 v185, v140
	v_min_f32_e32 v140, 0x60ad78ec, v172
	v_exp_f32_e32 v141, v141
	v_add_f32_e32 v140, 1.0, v140
	v_rcp_f32_e32 v172, v140
	v_min_f32_e32 v140, 0x60ad78ec, v173
	v_add_f32_e32 v140, 1.0, v140
	v_min_f32_e32 v171, 0x60ad78ec, v141
	v_rcp_f32_e32 v173, v140
	s_waitcnt vmcnt(8)
	v_lshlrev_b32_e32 v140, 16, v168
	v_lshlrev_b32_e32 v141, 16, v166
	v_add_f32_e32 v140, v136, v140
	v_add_f32_e32 v141, v132, v141
	v_mul_f32_e32 v140, 0xbfb8aa3b, v140
	v_mul_f32_e32 v141, 0xbfb8aa3b, v141
	v_exp_f32_e32 v140, v140
	v_exp_f32_e32 v141, v141
	v_pk_add_f32 v[170:171], v[170:171], 1.0 op_sel_hi:[1,0]
	v_and_b32_e32 v166, 0xffff0000, v166
	v_pk_mul_f32 v[170:171], v[170:171], v[172:173]
	v_add_f32_e32 v166, v133, v166
	v_pk_mul_f32 v[94:95], v[94:95], v[170:171]
	v_min_f32_e32 v170, 0x60ad78ec, v140
	v_min_f32_e32 v140, 0x60ad78ec, v141
	v_and_b32_e32 v141, 0xffff0000, v168
	v_add_f32_e32 v141, v137, v141
	v_mul_f32_e32 v141, 0xbfb8aa3b, v141
	v_exp_f32_e32 v141, v141
	v_mul_f32_e32 v166, 0xbfb8aa3b, v166
	v_exp_f32_e32 v166, v166
	v_add_f32_e32 v140, 1.0, v140
	v_min_f32_e32 v171, 0x60ad78ec, v141
	v_lshlrev_b32_e32 v141, 16, v169
	v_add_f32_e32 v141, v138, v141
	v_mul_f32_e32 v141, 0xbfb8aa3b, v141
	v_rcp_f32_e32 v172, v140
	v_min_f32_e32 v140, 0x60ad78ec, v166
	v_exp_f32_e32 v141, v141
	v_lshlrev_b32_e32 v166, 16, v167
	v_add_f32_e32 v166, v134, v166
	v_mul_f32_e32 v166, 0xbfb8aa3b, v166
	v_and_b32_e32 v167, 0xffff0000, v167
	v_exp_f32_e32 v168, v166
	v_add_f32_e32 v167, v135, v167
	v_min_f32_e32 v166, 0x60ad78ec, v141
	v_and_b32_e32 v141, 0xffff0000, v169
	v_mul_f32_e32 v167, 0xbfb8aa3b, v167
	v_add_f32_e32 v141, v139, v141
	v_exp_f32_e32 v169, v167
	v_add_f32_e32 v140, 1.0, v140
	v_mul_f32_e32 v141, 0xbfb8aa3b, v141
	v_rcp_f32_e32 v173, v140
	v_min_f32_e32 v140, 0x60ad78ec, v168
	v_exp_f32_e32 v141, v141
	v_add_f32_e32 v140, 1.0, v140
	v_rcp_f32_e32 v168, v140
	v_min_f32_e32 v140, 0x60ad78ec, v169
	v_add_f32_e32 v140, 1.0, v140
	v_min_f32_e32 v167, 0x60ad78ec, v141
	v_rcp_f32_e32 v169, v140
	s_waitcnt vmcnt(6)
	v_lshlrev_b32_e32 v140, 16, v164
	v_lshlrev_b32_e32 v141, 16, v162
	v_add_f32_e32 v140, v136, v140
	v_add_f32_e32 v141, v132, v141
	v_mul_f32_e32 v140, 0xbfb8aa3b, v140
	v_mul_f32_e32 v141, 0xbfb8aa3b, v141
	v_exp_f32_e32 v140, v140
	v_exp_f32_e32 v141, v141
	v_pk_add_f32 v[166:167], v[166:167], 1.0 op_sel_hi:[1,0]
	v_and_b32_e32 v162, 0xffff0000, v162
	v_pk_mul_f32 v[166:167], v[166:167], v[168:169]
	v_add_f32_e32 v162, v133, v162
	v_pk_mul_f32 v[78:79], v[78:79], v[166:167]
	v_min_f32_e32 v166, 0x60ad78ec, v140
	v_min_f32_e32 v140, 0x60ad78ec, v141
	v_and_b32_e32 v141, 0xffff0000, v164
	v_add_f32_e32 v141, v137, v141
	v_mul_f32_e32 v141, 0xbfb8aa3b, v141
	v_exp_f32_e32 v141, v141
	v_mul_f32_e32 v162, 0xbfb8aa3b, v162
	v_exp_f32_e32 v162, v162
	v_add_f32_e32 v140, 1.0, v140
	v_min_f32_e32 v167, 0x60ad78ec, v141
	v_lshlrev_b32_e32 v141, 16, v165
	v_add_f32_e32 v141, v138, v141
	v_mul_f32_e32 v141, 0xbfb8aa3b, v141
	v_rcp_f32_e32 v168, v140
	v_min_f32_e32 v140, 0x60ad78ec, v162
	v_exp_f32_e32 v141, v141
	v_lshlrev_b32_e32 v162, 16, v163
	v_add_f32_e32 v162, v134, v162
	v_mul_f32_e32 v162, 0xbfb8aa3b, v162
	v_and_b32_e32 v163, 0xffff0000, v163
	v_exp_f32_e32 v164, v162
	v_add_f32_e32 v163, v135, v163
	v_min_f32_e32 v162, 0x60ad78ec, v141
	v_and_b32_e32 v141, 0xffff0000, v165
	v_mul_f32_e32 v163, 0xbfb8aa3b, v163
	v_add_f32_e32 v141, v139, v141
	v_exp_f32_e32 v165, v163
	v_add_f32_e32 v140, 1.0, v140
	v_mul_f32_e32 v141, 0xbfb8aa3b, v141
	v_rcp_f32_e32 v169, v140
	v_min_f32_e32 v140, 0x60ad78ec, v164
	v_exp_f32_e32 v141, v141
	v_add_f32_e32 v140, 1.0, v140
	v_rcp_f32_e32 v164, v140
	v_min_f32_e32 v140, 0x60ad78ec, v165
	v_add_f32_e32 v140, 1.0, v140
	v_min_f32_e32 v163, 0x60ad78ec, v141
	v_rcp_f32_e32 v165, v140
	s_waitcnt vmcnt(4)
	v_lshlrev_b32_e32 v140, 16, v160
	v_lshlrev_b32_e32 v141, 16, v158
	v_add_f32_e32 v140, v136, v140
	v_add_f32_e32 v141, v132, v141
	v_mul_f32_e32 v140, 0xbfb8aa3b, v140
	v_mul_f32_e32 v141, 0xbfb8aa3b, v141
	v_exp_f32_e32 v140, v140
	v_exp_f32_e32 v141, v141
	v_pk_add_f32 v[162:163], v[162:163], 1.0 op_sel_hi:[1,0]
	v_and_b32_e32 v158, 0xffff0000, v158
	v_pk_mul_f32 v[162:163], v[162:163], v[164:165]
	v_add_f32_e32 v158, v133, v158
	v_pk_mul_f32 v[62:63], v[62:63], v[162:163]
	v_min_f32_e32 v162, 0x60ad78ec, v140
	v_min_f32_e32 v140, 0x60ad78ec, v141
	v_and_b32_e32 v141, 0xffff0000, v160
	v_add_f32_e32 v141, v137, v141
	v_mul_f32_e32 v141, 0xbfb8aa3b, v141
	v_exp_f32_e32 v141, v141
	v_mul_f32_e32 v158, 0xbfb8aa3b, v158
	v_exp_f32_e32 v158, v158
	v_add_f32_e32 v140, 1.0, v140
	v_min_f32_e32 v163, 0x60ad78ec, v141
	v_lshlrev_b32_e32 v141, 16, v161
	v_add_f32_e32 v141, v138, v141
	v_mul_f32_e32 v141, 0xbfb8aa3b, v141
	v_rcp_f32_e32 v164, v140
	v_min_f32_e32 v140, 0x60ad78ec, v158
	v_exp_f32_e32 v141, v141
	v_lshlrev_b32_e32 v158, 16, v159
	v_add_f32_e32 v158, v134, v158
	v_mul_f32_e32 v158, 0xbfb8aa3b, v158
	v_and_b32_e32 v159, 0xffff0000, v159
	v_exp_f32_e32 v160, v158
	v_add_f32_e32 v159, v135, v159
	v_min_f32_e32 v158, 0x60ad78ec, v141
	v_and_b32_e32 v141, 0xffff0000, v161
	v_mul_f32_e32 v159, 0xbfb8aa3b, v159
	v_add_f32_e32 v141, v139, v141
	v_exp_f32_e32 v161, v159
	v_add_f32_e32 v140, 1.0, v140
	v_mul_f32_e32 v141, 0xbfb8aa3b, v141
	v_rcp_f32_e32 v165, v140
	v_min_f32_e32 v140, 0x60ad78ec, v160
	v_exp_f32_e32 v141, v141
	v_add_f32_e32 v140, 1.0, v140
	v_rcp_f32_e32 v160, v140
	v_min_f32_e32 v140, 0x60ad78ec, v161
	v_add_f32_e32 v140, 1.0, v140
	v_min_f32_e32 v159, 0x60ad78ec, v141
	v_rcp_f32_e32 v161, v140
	s_waitcnt vmcnt(2)
	v_lshlrev_b32_e32 v140, 16, v156
	v_lshlrev_b32_e32 v141, 16, v154
	v_add_f32_e32 v140, v136, v140
	v_add_f32_e32 v141, v132, v141
	v_mul_f32_e32 v140, 0xbfb8aa3b, v140
	v_mul_f32_e32 v141, 0xbfb8aa3b, v141
	v_exp_f32_e32 v140, v140
	v_exp_f32_e32 v141, v141
	v_pk_add_f32 v[158:159], v[158:159], 1.0 op_sel_hi:[1,0]
	v_and_b32_e32 v154, 0xffff0000, v154
	v_pk_mul_f32 v[158:159], v[158:159], v[160:161]
	v_add_f32_e32 v154, v133, v154
	v_pk_mul_f32 v[46:47], v[46:47], v[158:159]
	v_min_f32_e32 v158, 0x60ad78ec, v140
	v_min_f32_e32 v140, 0x60ad78ec, v141
	v_and_b32_e32 v141, 0xffff0000, v156
	v_add_f32_e32 v141, v137, v141
	v_mul_f32_e32 v141, 0xbfb8aa3b, v141
	v_exp_f32_e32 v141, v141
	v_mul_f32_e32 v154, 0xbfb8aa3b, v154
	v_exp_f32_e32 v154, v154
	v_add_f32_e32 v140, 1.0, v140
	v_min_f32_e32 v159, 0x60ad78ec, v141
	v_lshlrev_b32_e32 v141, 16, v157
	v_add_f32_e32 v141, v138, v141
	v_rcp_f32_e32 v160, v140
	v_min_f32_e32 v140, 0x60ad78ec, v154
	v_mul_f32_e32 v141, 0xbfb8aa3b, v141
	v_lshlrev_b32_e32 v154, 16, v155
	v_exp_f32_e32 v141, v141
	v_add_f32_e32 v154, v134, v154
	v_mul_f32_e32 v154, 0xbfb8aa3b, v154
	v_and_b32_e32 v155, 0xffff0000, v155
	v_exp_f32_e32 v156, v154
	v_add_f32_e32 v155, v135, v155
	v_mul_f32_e32 v155, 0xbfb8aa3b, v155
	v_min_f32_e32 v154, 0x60ad78ec, v141
	v_and_b32_e32 v141, 0xffff0000, v157
	v_exp_f32_e32 v157, v155
	v_add_f32_e32 v140, 1.0, v140
	v_rcp_f32_e32 v161, v140
	v_min_f32_e32 v140, 0x60ad78ec, v156
	v_add_f32_e32 v140, 1.0, v140
	v_rcp_f32_e32 v156, v140
	v_min_f32_e32 v140, 0x60ad78ec, v157
	v_add_f32_e32 v140, 1.0, v140
	v_rcp_f32_e32 v157, v140
	s_waitcnt vmcnt(0)
	v_lshlrev_b32_e32 v140, 16, v152
	v_add_f32_e32 v136, v136, v140
	v_lshlrev_b32_e32 v140, 16, v2
	v_add_f32_e32 v132, v132, v140
	v_mul_f32_e32 v136, 0xbfb8aa3b, v136
	v_mul_f32_e32 v132, 0xbfb8aa3b, v132
	v_exp_f32_e32 v136, v136
	v_exp_f32_e32 v140, v132
	v_and_b32_e32 v2, 0xffff0000, v2
	v_add_f32_e32 v2, v133, v2
	v_min_f32_e32 v132, 0x60ad78ec, v136
	v_min_f32_e32 v136, 0x60ad78ec, v140
	v_and_b32_e32 v140, 0xffff0000, v152
	v_add_f32_e32 v137, v137, v140
	v_mul_f32_e32 v137, 0xbfb8aa3b, v137
	v_exp_f32_e32 v137, v137
	v_add_f32_e32 v133, 1.0, v136
	v_mul_f32_e32 v2, 0xbfb8aa3b, v2
	v_rcp_f32_e32 v136, v133
	v_min_f32_e32 v133, 0x60ad78ec, v137
	v_lshlrev_b32_e32 v137, 16, v153
	v_exp_f32_e32 v2, v2
	v_add_f32_e32 v137, v138, v137
	v_mul_f32_e32 v137, 0xbfb8aa3b, v137
	v_exp_f32_e32 v138, v137
	v_lshlrev_b32_e32 v137, 16, v3
	v_and_b32_e32 v3, 0xffff0000, v3
	v_add_f32_e32 v134, v134, v137
	v_add_f32_e32 v3, v135, v3
	v_min_f32_e32 v2, 0x60ad78ec, v2
	v_mul_f32_e32 v134, 0xbfb8aa3b, v134
	v_mul_f32_e32 v3, 0xbfb8aa3b, v3
	v_exp_f32_e32 v134, v134
	v_add_f32_e32 v2, 1.0, v2
	v_exp_f32_e32 v135, v3
	v_rcp_f32_e32 v137, v2
	v_min_f32_e32 v2, 0x60ad78ec, v138
	v_and_b32_e32 v138, 0xffff0000, v153
	v_add_f32_e32 v138, v139, v138
	v_mul_f32_e32 v138, 0xbfb8aa3b, v138
	v_min_f32_e32 v134, 0x60ad78ec, v134
	v_exp_f32_e32 v138, v138
	v_min_f32_e32 v135, 0x60ad78ec, v135
	v_add_f32_e32 v141, v139, v141
	v_add_f32_e32 v3, 1.0, v134
	v_add_f32_e32 v135, 1.0, v135
	v_mul_f32_e32 v141, 0xbfb8aa3b, v141
	v_rcp_f32_e32 v134, v3
	v_rcp_f32_e32 v135, v135
	v_exp_f32_e32 v141, v141
	v_min_f32_e32 v3, 0x60ad78ec, v138
	v_pk_add_f32 v[2:3], v[2:3], 1.0 op_sel_hi:[1,0]
	v_pk_add_f32 v[132:133], v[132:133], 1.0 op_sel_hi:[1,0]
	v_pk_mul_f32 v[2:3], v[2:3], v[134:135]
	v_min_f32_e32 v155, 0x60ad78ec, v141
	v_pk_mul_f32 v[14:15], v[14:15], v[2:3]
	v_add_u32_e32 v2, s82, v0
	v_pk_add_f32 v[154:155], v[154:155], 1.0 op_sel_hi:[1,0]
	v_ashrrev_i32_e32 v3, 31, v2
	v_pk_mul_f32 v[154:155], v[154:155], v[156:157]
	v_pk_mul_f32 v[152:153], v[132:133], v[136:137]
	v_lshl_add_u64 v[136:137], v[2:3], 2, s[6:7]
	v_lshlrev_b64 v[2:3], 1, v[2:3]
	v_pk_mul_f32 v[30:31], v[30:31], v[154:155]
	v_mad_i64_i32 v[154:155], vcc, v174, s2, v[2:3]
	v_lshl_add_u64 v[154:155], s[30:31], 0, v[154:155]
	v_add_co_u32_e32 v156, vcc, s76, v154
	v_pk_add_f32 v[182:183], v[182:183], 1.0 op_sel_hi:[1,0]
	s_nop 0
	v_addc_co_u32_e32 v157, vcc, 0, v155, vcc
	v_add_co_u32_e32 v154, vcc, s77, v154
	v_pk_mul_f32 v[182:183], v[182:183], v[184:185]
	s_nop 0
	v_addc_co_u32_e32 v155, vcc, 0, v155, vcc
	v_pk_mul_f32 v[92:93], v[92:93], v[182:183]
	v_pk_add_f32 v[158:159], v[158:159], 1.0 op_sel_hi:[1,0]
	global_load_dwordx4 v[132:135], v[136:137], off offset:-4096
	s_nop 0
	global_load_dwordx4 v[136:139], v[136:137], off
	v_pk_mul_f32 v[158:159], v[158:159], v[160:161]
	global_load_dwordx2 v[182:183], v[154:155], off offset:1024
	v_mad_i64_i32 v[154:155], vcc, v175, s2, v[2:3]
	v_lshl_add_u64 v[154:155], s[30:31], 0, v[154:155]
	v_pk_mul_f32 v[28:29], v[28:29], v[158:159]
	v_add_co_u32_e32 v158, vcc, s76, v154
	v_pk_mul_f32 v[12:13], v[12:13], v[152:153]
	s_nop 0
	v_addc_co_u32_e32 v159, vcc, 0, v155, vcc
	v_add_co_u32_e32 v154, vcc, s77, v154
	v_pk_add_f32 v[170:171], v[170:171], 1.0 op_sel_hi:[1,0]
	s_nop 0
	v_addc_co_u32_e32 v155, vcc, 0, v155, vcc
	global_load_dwordx2 v[184:185], v[158:159], off offset:3072
	global_load_dwordx2 v[186:187], v[154:155], off offset:1024
	global_load_dwordx2 v[188:189], v[156:157], off offset:3072
	v_mad_i64_i32 v[152:153], vcc, v176, s2, v[2:3]
	v_lshl_add_u64 v[152:153], s[30:31], 0, v[152:153]
	v_add_co_u32_e32 v154, vcc, s76, v152
	v_pk_add_f32 v[166:167], v[166:167], 1.0 op_sel_hi:[1,0]
	s_nop 0
	v_addc_co_u32_e32 v155, vcc, 0, v153, vcc
	v_add_co_u32_e32 v152, vcc, s77, v152
	v_pk_mul_f32 v[170:171], v[170:171], v[172:173]
	s_nop 0
	v_addc_co_u32_e32 v153, vcc, 0, v153, vcc
	v_mad_i64_i32 v[156:157], vcc, v177, s2, v[2:3]
	v_lshl_add_u64 v[156:157], s[30:31], 0, v[156:157]
	v_add_co_u32_e32 v158, vcc, s76, v156
	v_pk_mul_f32 v[166:167], v[166:167], v[168:169]
	s_nop 0
	v_addc_co_u32_e32 v159, vcc, 0, v157, vcc
	v_add_co_u32_e32 v156, vcc, s77, v156
	v_pk_mul_f32 v[76:77], v[76:77], v[170:171]
	v_pk_mul_f32 v[60:61], v[60:61], v[166:167]
	v_addc_co_u32_e32 v157, vcc, 0, v157, vcc
	global_load_dwordx2 v[170:171], v[154:155], off offset:3072
	global_load_dwordx2 v[172:173], v[152:153], off offset:1024
	global_load_dwordx2 v[166:167], v[158:159], off offset:3072
	global_load_dwordx2 v[168:169], v[156:157], off offset:1024
	v_mad_i64_i32 v[152:153], vcc, v178, s2, v[2:3]
	v_lshl_add_u64 v[152:153], s[30:31], 0, v[152:153]
	v_add_co_u32_e32 v154, vcc, s76, v152
	v_pk_add_f32 v[162:163], v[162:163], 1.0 op_sel_hi:[1,0]
	s_nop 0
	v_addc_co_u32_e32 v155, vcc, 0, v153, vcc
	v_add_co_u32_e32 v152, vcc, s77, v152
	v_pk_mul_f32 v[162:163], v[162:163], v[164:165]
	s_nop 0
	v_addc_co_u32_e32 v153, vcc, 0, v153, vcc
	v_mad_i64_i32 v[156:157], vcc, v179, s2, v[2:3]
	v_lshl_add_u64 v[156:157], s[30:31], 0, v[156:157]
	v_add_co_u32_e32 v158, vcc, s76, v156
	v_pk_mul_f32 v[44:45], v[44:45], v[162:163]
	s_nop 0
	v_addc_co_u32_e32 v159, vcc, 0, v157, vcc
	v_add_co_u32_e32 v156, vcc, s77, v156
	v_pk_mul_f32 v[124:125], v[124:125], v[190:191]
	s_nop 0
	v_addc_co_u32_e32 v157, vcc, 0, v157, vcc
	global_load_dwordx2 v[162:163], v[154:155], off offset:3072
	global_load_dwordx2 v[164:165], v[152:153], off offset:1024
	s_nop 0
	global_load_dwordx2 v[158:159], v[158:159], off offset:3072
	s_nop 0
	global_load_dwordx2 v[160:161], v[156:157], off offset:1024
	v_mad_i64_i32 v[152:153], vcc, v180, s2, v[2:3]
	v_lshl_add_u64 v[152:153], s[30:31], 0, v[152:153]
	v_add_co_u32_e32 v154, vcc, s76, v152
	s_nop 1
	v_addc_co_u32_e32 v155, vcc, 0, v153, vcc
	v_add_co_u32_e32 v152, vcc, s77, v152
	s_nop 1
	v_addc_co_u32_e32 v153, vcc, 0, v153, vcc
	v_mad_i64_i32 v[2:3], vcc, v181, s2, v[2:3]
	v_lshl_add_u64 v[2:3], s[30:31], 0, v[2:3]
	v_add_co_u32_e32 v190, vcc, s76, v2
	s_nop 1
	v_addc_co_u32_e32 v191, vcc, 0, v3, vcc
	v_add_co_u32_e32 v192, vcc, s77, v2
	s_waitcnt vmcnt(11)
	v_lshlrev_b32_e32 v2, 16, v182
	v_add_f32_e32 v2, v136, v2
	v_mul_f32_e32 v2, 0xbfb8aa3b, v2
	v_exp_f32_e32 v140, v2
	s_waitcnt vmcnt(8)
	v_lshlrev_b32_e32 v2, 16, v188
	v_add_f32_e32 v2, v132, v2
	v_mul_f32_e32 v2, 0xbfb8aa3b, v2
	v_exp_f32_e32 v141, v2
	v_addc_co_u32_e32 v193, vcc, 0, v3, vcc
	global_load_dwordx2 v[154:155], v[154:155], off offset:3072
	s_nop 0
	global_load_dwordx2 v[156:157], v[152:153], off offset:1024
	global_load_dwordx2 v[2:3], v[190:191], off offset:3072
	s_nop 0
	global_load_dwordx2 v[152:153], v[192:193], off offset:1024
	v_min_f32_e32 v190, 0x60ad78ec, v140
	v_min_f32_e32 v140, 0x60ad78ec, v141
	v_and_b32_e32 v141, 0xffff0000, v182
	v_add_f32_e32 v141, v137, v141
	v_mul_f32_e32 v141, 0xbfb8aa3b, v141
	v_exp_f32_e32 v141, v141
	v_and_b32_e32 v182, 0xffff0000, v188
	v_add_f32_e32 v182, v133, v182
	v_mul_f32_e32 v182, 0xbfb8aa3b, v182
	v_exp_f32_e32 v182, v182
	v_min_f32_e32 v191, 0x60ad78ec, v141
	v_lshlrev_b32_e32 v141, 16, v183
	v_add_f32_e32 v141, v138, v141
	v_mul_f32_e32 v141, 0xbfb8aa3b, v141
	v_add_f32_e32 v140, 1.0, v140
	v_exp_f32_e32 v141, v141
	v_rcp_f32_e32 v192, v140
	v_min_f32_e32 v140, 0x60ad78ec, v182
	v_lshlrev_b32_e32 v182, 16, v189
	v_add_f32_e32 v182, v134, v182
	v_mul_f32_e32 v182, 0xbfb8aa3b, v182
	v_exp_f32_e32 v188, v182
	v_min_f32_e32 v182, 0x60ad78ec, v141
	v_and_b32_e32 v141, 0xffff0000, v183
	v_and_b32_e32 v183, 0xffff0000, v189
	v_add_f32_e32 v183, v135, v183
	v_mul_f32_e32 v183, 0xbfb8aa3b, v183
	v_add_f32_e32 v141, v139, v141
	v_exp_f32_e32 v189, v183
	v_add_f32_e32 v140, 1.0, v140
	v_mul_f32_e32 v141, 0xbfb8aa3b, v141
	v_rcp_f32_e32 v193, v140
	v_min_f32_e32 v140, 0x60ad78ec, v188
	v_exp_f32_e32 v141, v141
	v_add_f32_e32 v140, 1.0, v140
	v_rcp_f32_e32 v188, v140
	v_min_f32_e32 v140, 0x60ad78ec, v189
	v_add_f32_e32 v140, 1.0, v140
	v_min_f32_e32 v183, 0x60ad78ec, v141
	v_rcp_f32_e32 v189, v140
	v_lshlrev_b32_e32 v140, 16, v186
	v_lshlrev_b32_e32 v141, 16, v184
	v_add_f32_e32 v140, v136, v140
	v_add_f32_e32 v141, v132, v141
	v_mul_f32_e32 v140, 0xbfb8aa3b, v140
	v_mul_f32_e32 v141, 0xbfb8aa3b, v141
	v_exp_f32_e32 v140, v140
	v_exp_f32_e32 v141, v141
	v_pk_add_f32 v[182:183], v[182:183], 1.0 op_sel_hi:[1,0]
	v_pk_add_f32 v[190:191], v[190:191], 1.0 op_sel_hi:[1,0]
	v_pk_mul_f32 v[182:183], v[182:183], v[188:189]
	v_pk_mul_f32 v[190:191], v[190:191], v[192:193]
	v_pk_mul_f32 v[122:123], v[122:123], v[182:183]
	v_min_f32_e32 v182, 0x60ad78ec, v140
	v_min_f32_e32 v140, 0x60ad78ec, v141
	v_and_b32_e32 v141, 0xffff0000, v186
	v_add_f32_e32 v141, v137, v141
	v_mul_f32_e32 v141, 0xbfb8aa3b, v141
	v_exp_f32_e32 v141, v141
	v_and_b32_e32 v183, 0xffff0000, v184
	v_add_f32_e32 v183, v133, v183
	v_mul_f32_e32 v183, 0xbfb8aa3b, v183
	v_exp_f32_e32 v184, v183
	v_min_f32_e32 v183, 0x60ad78ec, v141
	v_lshlrev_b32_e32 v141, 16, v187
	v_add_f32_e32 v141, v138, v141
	v_add_f32_e32 v140, 1.0, v140
	v_mul_f32_e32 v141, 0xbfb8aa3b, v141
	v_rcp_f32_e32 v188, v140
	v_min_f32_e32 v140, 0x60ad78ec, v184
	v_exp_f32_e32 v141, v141
	v_lshlrev_b32_e32 v184, 16, v185
	v_add_f32_e32 v184, v134, v184
	v_mul_f32_e32 v184, 0xbfb8aa3b, v184
	v_and_b32_e32 v185, 0xffff0000, v185
	v_exp_f32_e32 v186, v184
	v_add_f32_e32 v185, v135, v185
	v_min_f32_e32 v184, 0x60ad78ec, v141
	v_and_b32_e32 v141, 0xffff0000, v187
	v_mul_f32_e32 v185, 0xbfb8aa3b, v185
	v_add_f32_e32 v141, v139, v141
	v_exp_f32_e32 v187, v185
	v_add_f32_e32 v140, 1.0, v140
	v_mul_f32_e32 v141, 0xbfb8aa3b, v141
	v_rcp_f32_e32 v189, v140
	v_min_f32_e32 v140, 0x60ad78ec, v186
	v_exp_f32_e32 v141, v141
	v_add_f32_e32 v140, 1.0, v140
	v_rcp_f32_e32 v186, v140
	v_min_f32_e32 v140, 0x60ad78ec, v187
	v_add_f32_e32 v140, 1.0, v140
	v_min_f32_e32 v185, 0x60ad78ec, v141
	v_rcp_f32_e32 v187, v140
	s_waitcnt vmcnt(10)
	v_lshlrev_b32_e32 v140, 16, v172
	v_lshlrev_b32_e32 v141, 16, v170
	v_add_f32_e32 v140, v136, v140
	v_add_f32_e32 v141, v132, v141
	v_mul_f32_e32 v140, 0xbfb8aa3b, v140
	v_mul_f32_e32 v141, 0xbfb8aa3b, v141
	v_exp_f32_e32 v140, v140
	v_exp_f32_e32 v141, v141
	v_pk_add_f32 v[182:183], v[182:183], 1.0 op_sel_hi:[1,0]
	v_and_b32_e32 v170, 0xffff0000, v170
	v_pk_mul_f32 v[182:183], v[182:183], v[188:189]
	v_add_f32_e32 v170, v133, v170
	v_pk_mul_f32 v[104:105], v[104:105], v[182:183]
	v_min_f32_e32 v182, 0x60ad78ec, v140
	v_min_f32_e32 v140, 0x60ad78ec, v141
	v_and_b32_e32 v141, 0xffff0000, v172
	v_add_f32_e32 v141, v137, v141
	v_mul_f32_e32 v141, 0xbfb8aa3b, v141
	v_exp_f32_e32 v141, v141
	v_mul_f32_e32 v170, 0xbfb8aa3b, v170
	v_exp_f32_e32 v170, v170
	v_pk_add_f32 v[184:185], v[184:185], 1.0 op_sel_hi:[1,0]
	v_min_f32_e32 v183, 0x60ad78ec, v141
	v_lshlrev_b32_e32 v141, 16, v173
	v_add_f32_e32 v141, v138, v141
	v_pk_mul_f32 v[184:185], v[184:185], v[186:187]
	v_add_f32_e32 v140, 1.0, v140
	v_mul_f32_e32 v141, 0xbfb8aa3b, v141
	v_pk_mul_f32 v[106:107], v[106:107], v[184:185]
	v_rcp_f32_e32 v184, v140
	v_min_f32_e32 v140, 0x60ad78ec, v170
	v_exp_f32_e32 v141, v141
	v_lshlrev_b32_e32 v170, 16, v171
	v_add_f32_e32 v170, v134, v170
	v_mul_f32_e32 v170, 0xbfb8aa3b, v170
	v_and_b32_e32 v171, 0xffff0000, v171
	v_exp_f32_e32 v172, v170
	v_add_f32_e32 v171, v135, v171
	v_min_f32_e32 v170, 0x60ad78ec, v141
	v_and_b32_e32 v141, 0xffff0000, v173
	v_mul_f32_e32 v171, 0xbfb8aa3b, v171
	v_add_f32_e32 v141, v139, v141
	v_exp_f32_e32 v173, v171
	v_add_f32_e32 v140, 1.0, v140
	v_mul_f32_e32 v141, 0xbfb8aa3b, v141
	v_rcp_f32_e32 v185, v140
	v_min_f32_e32 v140, 0x60ad78ec, v172
	v_exp_f32_e32 v141, v141
	v_add_f32_e32 v140, 1.0, v140
	v_rcp_f32_e32 v172, v140
	v_min_f32_e32 v140, 0x60ad78ec, v173
	v_add_f32_e32 v140, 1.0, v140
	v_min_f32_e32 v171, 0x60ad78ec, v141
	v_rcp_f32_e32 v173, v140
	s_waitcnt vmcnt(8)
	v_lshlrev_b32_e32 v140, 16, v168
	v_lshlrev_b32_e32 v141, 16, v166
	v_add_f32_e32 v140, v136, v140
	v_add_f32_e32 v141, v132, v141
	v_mul_f32_e32 v140, 0xbfb8aa3b, v140
	v_mul_f32_e32 v141, 0xbfb8aa3b, v141
	v_exp_f32_e32 v140, v140
	v_exp_f32_e32 v141, v141
	v_pk_add_f32 v[170:171], v[170:171], 1.0 op_sel_hi:[1,0]
	v_and_b32_e32 v166, 0xffff0000, v166
	v_pk_mul_f32 v[170:171], v[170:171], v[172:173]
	v_add_f32_e32 v166, v133, v166
	v_pk_mul_f32 v[90:91], v[90:91], v[170:171]
	v_min_f32_e32 v170, 0x60ad78ec, v140
	v_min_f32_e32 v140, 0x60ad78ec, v141
	v_and_b32_e32 v141, 0xffff0000, v168
	v_add_f32_e32 v141, v137, v141
	v_mul_f32_e32 v141, 0xbfb8aa3b, v141
	v_exp_f32_e32 v141, v141
	v_mul_f32_e32 v166, 0xbfb8aa3b, v166
	v_exp_f32_e32 v166, v166
	v_add_f32_e32 v140, 1.0, v140
	v_min_f32_e32 v171, 0x60ad78ec, v141
	v_lshlrev_b32_e32 v141, 16, v169
	v_add_f32_e32 v141, v138, v141
	v_mul_f32_e32 v141, 0xbfb8aa3b, v141
	v_rcp_f32_e32 v172, v140
	v_min_f32_e32 v140, 0x60ad78ec, v166
	v_exp_f32_e32 v141, v141
	v_lshlrev_b32_e32 v166, 16, v167
	v_add_f32_e32 v166, v134, v166
	v_mul_f32_e32 v166, 0xbfb8aa3b, v166
	v_and_b32_e32 v167, 0xffff0000, v167
	v_exp_f32_e32 v168, v166
	v_add_f32_e32 v167, v135, v167
	v_min_f32_e32 v166, 0x60ad78ec, v141
	v_and_b32_e32 v141, 0xffff0000, v169
	v_mul_f32_e32 v167, 0xbfb8aa3b, v167
	v_add_f32_e32 v141, v139, v141
	v_exp_f32_e32 v169, v167
	v_add_f32_e32 v140, 1.0, v140
	v_mul_f32_e32 v141, 0xbfb8aa3b, v141
	v_rcp_f32_e32 v173, v140
	v_min_f32_e32 v140, 0x60ad78ec, v168
	v_exp_f32_e32 v141, v141
	v_add_f32_e32 v140, 1.0, v140
	v_rcp_f32_e32 v168, v140
	v_min_f32_e32 v140, 0x60ad78ec, v169
	v_add_f32_e32 v140, 1.0, v140
	v_min_f32_e32 v167, 0x60ad78ec, v141
	v_rcp_f32_e32 v169, v140
	s_waitcnt vmcnt(6)
	v_lshlrev_b32_e32 v140, 16, v164
	v_lshlrev_b32_e32 v141, 16, v162
	v_add_f32_e32 v140, v136, v140
	v_add_f32_e32 v141, v132, v141
	v_mul_f32_e32 v140, 0xbfb8aa3b, v140
	v_mul_f32_e32 v141, 0xbfb8aa3b, v141
	v_exp_f32_e32 v140, v140
	v_exp_f32_e32 v141, v141
	v_pk_add_f32 v[166:167], v[166:167], 1.0 op_sel_hi:[1,0]
	v_and_b32_e32 v162, 0xffff0000, v162
	v_pk_mul_f32 v[166:167], v[166:167], v[168:169]
	v_add_f32_e32 v162, v133, v162
	v_pk_mul_f32 v[74:75], v[74:75], v[166:167]
	v_min_f32_e32 v166, 0x60ad78ec, v140
	v_min_f32_e32 v140, 0x60ad78ec, v141
	v_and_b32_e32 v141, 0xffff0000, v164
	v_add_f32_e32 v141, v137, v141
	v_mul_f32_e32 v141, 0xbfb8aa3b, v141
	v_exp_f32_e32 v141, v141
	v_mul_f32_e32 v162, 0xbfb8aa3b, v162
	v_exp_f32_e32 v162, v162
	v_add_f32_e32 v140, 1.0, v140
	v_min_f32_e32 v167, 0x60ad78ec, v141
	v_lshlrev_b32_e32 v141, 16, v165
	v_add_f32_e32 v141, v138, v141
	v_mul_f32_e32 v141, 0xbfb8aa3b, v141
	v_rcp_f32_e32 v168, v140
	v_min_f32_e32 v140, 0x60ad78ec, v162
	v_exp_f32_e32 v141, v141
	v_lshlrev_b32_e32 v162, 16, v163
	v_add_f32_e32 v162, v134, v162
	v_mul_f32_e32 v162, 0xbfb8aa3b, v162
	v_and_b32_e32 v163, 0xffff0000, v163
	v_exp_f32_e32 v164, v162
	v_add_f32_e32 v163, v135, v163
	v_min_f32_e32 v162, 0x60ad78ec, v141
	v_and_b32_e32 v141, 0xffff0000, v165
	v_mul_f32_e32 v163, 0xbfb8aa3b, v163
	v_add_f32_e32 v141, v139, v141
	v_exp_f32_e32 v165, v163
	v_add_f32_e32 v140, 1.0, v140
	v_mul_f32_e32 v141, 0xbfb8aa3b, v141
	v_rcp_f32_e32 v169, v140
	v_min_f32_e32 v140, 0x60ad78ec, v164
	v_exp_f32_e32 v141, v141
	v_add_f32_e32 v140, 1.0, v140
	v_rcp_f32_e32 v164, v140
	v_min_f32_e32 v140, 0x60ad78ec, v165
	v_add_f32_e32 v140, 1.0, v140
	v_min_f32_e32 v163, 0x60ad78ec, v141
	v_rcp_f32_e32 v165, v140
	s_waitcnt vmcnt(4)
	v_lshlrev_b32_e32 v140, 16, v160
	v_lshlrev_b32_e32 v141, 16, v158
	v_add_f32_e32 v140, v136, v140
	v_add_f32_e32 v141, v132, v141
	v_mul_f32_e32 v140, 0xbfb8aa3b, v140
	v_mul_f32_e32 v141, 0xbfb8aa3b, v141
	v_exp_f32_e32 v140, v140
	v_exp_f32_e32 v141, v141
	v_pk_add_f32 v[162:163], v[162:163], 1.0 op_sel_hi:[1,0]
	v_and_b32_e32 v158, 0xffff0000, v158
	v_pk_mul_f32 v[162:163], v[162:163], v[164:165]
	v_add_f32_e32 v158, v133, v158
	v_pk_mul_f32 v[58:59], v[58:59], v[162:163]
	v_min_f32_e32 v162, 0x60ad78ec, v140
	v_min_f32_e32 v140, 0x60ad78ec, v141
	v_and_b32_e32 v141, 0xffff0000, v160
	v_add_f32_e32 v141, v137, v141
	v_mul_f32_e32 v141, 0xbfb8aa3b, v141
	v_exp_f32_e32 v141, v141
	v_mul_f32_e32 v158, 0xbfb8aa3b, v158
	v_exp_f32_e32 v158, v158
	v_add_f32_e32 v140, 1.0, v140
	v_min_f32_e32 v163, 0x60ad78ec, v141
	v_lshlrev_b32_e32 v141, 16, v161
	v_add_f32_e32 v141, v138, v141
	v_mul_f32_e32 v141, 0xbfb8aa3b, v141
	v_rcp_f32_e32 v164, v140
	v_min_f32_e32 v140, 0x60ad78ec, v158
	v_exp_f32_e32 v141, v141
	v_lshlrev_b32_e32 v158, 16, v159
	v_add_f32_e32 v158, v134, v158
	v_mul_f32_e32 v158, 0xbfb8aa3b, v158
	v_and_b32_e32 v159, 0xffff0000, v159
	v_exp_f32_e32 v160, v158
	v_add_f32_e32 v159, v135, v159
	v_min_f32_e32 v158, 0x60ad78ec, v141
	v_and_b32_e32 v141, 0xffff0000, v161
	v_mul_f32_e32 v159, 0xbfb8aa3b, v159
	v_add_f32_e32 v141, v139, v141
	v_exp_f32_e32 v161, v159
	v_add_f32_e32 v140, 1.0, v140
	v_mul_f32_e32 v141, 0xbfb8aa3b, v141
	v_rcp_f32_e32 v165, v140
	v_min_f32_e32 v140, 0x60ad78ec, v160
	v_exp_f32_e32 v141, v141
	v_add_f32_e32 v140, 1.0, v140
	v_rcp_f32_e32 v160, v140
	v_min_f32_e32 v140, 0x60ad78ec, v161
	v_add_f32_e32 v140, 1.0, v140
	v_min_f32_e32 v159, 0x60ad78ec, v141
	v_rcp_f32_e32 v161, v140
	s_waitcnt vmcnt(2)
	v_lshlrev_b32_e32 v140, 16, v156
	v_lshlrev_b32_e32 v141, 16, v154
	v_add_f32_e32 v140, v136, v140
	v_add_f32_e32 v141, v132, v141
	v_mul_f32_e32 v140, 0xbfb8aa3b, v140
	v_mul_f32_e32 v141, 0xbfb8aa3b, v141
	v_exp_f32_e32 v140, v140
	v_exp_f32_e32 v141, v141
	v_pk_add_f32 v[158:159], v[158:159], 1.0 op_sel_hi:[1,0]
	v_and_b32_e32 v154, 0xffff0000, v154
	v_pk_mul_f32 v[158:159], v[158:159], v[160:161]
	v_add_f32_e32 v154, v133, v154
	v_pk_mul_f32 v[42:43], v[42:43], v[158:159]
	v_min_f32_e32 v158, 0x60ad78ec, v140
	v_min_f32_e32 v140, 0x60ad78ec, v141
	v_and_b32_e32 v141, 0xffff0000, v156
	v_add_f32_e32 v141, v137, v141
	v_mul_f32_e32 v141, 0xbfb8aa3b, v141
	v_exp_f32_e32 v141, v141
	v_mul_f32_e32 v154, 0xbfb8aa3b, v154
	v_exp_f32_e32 v154, v154
	v_add_f32_e32 v140, 1.0, v140
	v_min_f32_e32 v159, 0x60ad78ec, v141
	v_lshlrev_b32_e32 v141, 16, v157
	v_add_f32_e32 v141, v138, v141
	v_rcp_f32_e32 v160, v140
	v_min_f32_e32 v140, 0x60ad78ec, v154
	v_mul_f32_e32 v141, 0xbfb8aa3b, v141
	v_lshlrev_b32_e32 v154, 16, v155
	v_exp_f32_e32 v141, v141
	v_add_f32_e32 v154, v134, v154
	v_mul_f32_e32 v154, 0xbfb8aa3b, v154
	v_and_b32_e32 v155, 0xffff0000, v155
	v_exp_f32_e32 v156, v154
	v_add_f32_e32 v155, v135, v155
	v_mul_f32_e32 v155, 0xbfb8aa3b, v155
	v_min_f32_e32 v154, 0x60ad78ec, v141
	v_and_b32_e32 v141, 0xffff0000, v157
	v_exp_f32_e32 v157, v155
	v_add_f32_e32 v140, 1.0, v140
	v_rcp_f32_e32 v161, v140
	v_min_f32_e32 v140, 0x60ad78ec, v156
	v_add_f32_e32 v140, 1.0, v140
	v_rcp_f32_e32 v156, v140
	v_min_f32_e32 v140, 0x60ad78ec, v157
	v_add_f32_e32 v140, 1.0, v140
	v_rcp_f32_e32 v157, v140
	s_waitcnt vmcnt(0)
	v_lshlrev_b32_e32 v140, 16, v152
	v_add_f32_e32 v136, v136, v140
	v_lshlrev_b32_e32 v140, 16, v2
	v_add_f32_e32 v132, v132, v140
	v_mul_f32_e32 v136, 0xbfb8aa3b, v136
	v_mul_f32_e32 v132, 0xbfb8aa3b, v132
	v_exp_f32_e32 v136, v136
	v_exp_f32_e32 v140, v132
	v_and_b32_e32 v2, 0xffff0000, v2
	v_add_f32_e32 v2, v133, v2
	v_min_f32_e32 v132, 0x60ad78ec, v136
	v_min_f32_e32 v136, 0x60ad78ec, v140
	v_and_b32_e32 v140, 0xffff0000, v152
	v_add_f32_e32 v137, v137, v140
	v_mul_f32_e32 v137, 0xbfb8aa3b, v137
	v_exp_f32_e32 v137, v137
	v_add_f32_e32 v133, 1.0, v136
	v_mul_f32_e32 v2, 0xbfb8aa3b, v2
	v_rcp_f32_e32 v136, v133
	v_min_f32_e32 v133, 0x60ad78ec, v137
	v_lshlrev_b32_e32 v137, 16, v153
	v_exp_f32_e32 v2, v2
	v_add_f32_e32 v137, v138, v137
	v_mul_f32_e32 v137, 0xbfb8aa3b, v137
	v_exp_f32_e32 v138, v137
	v_lshlrev_b32_e32 v137, 16, v3
	v_and_b32_e32 v3, 0xffff0000, v3
	v_add_f32_e32 v134, v134, v137
	v_add_f32_e32 v3, v135, v3
	v_min_f32_e32 v2, 0x60ad78ec, v2
	v_mul_f32_e32 v134, 0xbfb8aa3b, v134
	v_mul_f32_e32 v3, 0xbfb8aa3b, v3
	v_exp_f32_e32 v134, v134
	v_add_f32_e32 v2, 1.0, v2
	v_exp_f32_e32 v135, v3
	v_rcp_f32_e32 v137, v2
	v_min_f32_e32 v2, 0x60ad78ec, v138
	v_and_b32_e32 v138, 0xffff0000, v153
	v_add_f32_e32 v138, v139, v138
	v_mul_f32_e32 v138, 0xbfb8aa3b, v138
	v_min_f32_e32 v134, 0x60ad78ec, v134
	v_exp_f32_e32 v138, v138
	v_min_f32_e32 v135, 0x60ad78ec, v135
	v_add_f32_e32 v141, v139, v141
	v_add_f32_e32 v3, 1.0, v134
	v_add_f32_e32 v135, 1.0, v135
	v_mul_f32_e32 v141, 0xbfb8aa3b, v141
	v_rcp_f32_e32 v134, v3
	v_rcp_f32_e32 v135, v135
	v_exp_f32_e32 v141, v141
	v_min_f32_e32 v3, 0x60ad78ec, v138
	v_pk_add_f32 v[2:3], v[2:3], 1.0 op_sel_hi:[1,0]
	v_pk_add_f32 v[132:133], v[132:133], 1.0 op_sel_hi:[1,0]
	v_pk_mul_f32 v[2:3], v[2:3], v[134:135]
	v_min_f32_e32 v155, 0x60ad78ec, v141
	v_pk_mul_f32 v[10:11], v[10:11], v[2:3]
	v_add_u32_e32 v2, s83, v0
	v_pk_add_f32 v[154:155], v[154:155], 1.0 op_sel_hi:[1,0]
	v_ashrrev_i32_e32 v3, 31, v2
	v_pk_mul_f32 v[154:155], v[154:155], v[156:157]
	v_pk_mul_f32 v[152:153], v[132:133], v[136:137]
	v_lshl_add_u64 v[136:137], v[2:3], 2, s[6:7]
	v_lshlrev_b64 v[2:3], 1, v[2:3]
	v_pk_mul_f32 v[26:27], v[26:27], v[154:155]
	v_mad_i64_i32 v[154:155], vcc, v174, s2, v[2:3]
	v_lshl_add_u64 v[154:155], s[30:31], 0, v[154:155]
	v_add_co_u32_e32 v156, vcc, s76, v154
	v_pk_add_f32 v[182:183], v[182:183], 1.0 op_sel_hi:[1,0]
	s_nop 0
	v_addc_co_u32_e32 v157, vcc, 0, v155, vcc
	v_add_co_u32_e32 v154, vcc, s77, v154
	v_pk_mul_f32 v[182:183], v[182:183], v[184:185]
	s_nop 0
	v_addc_co_u32_e32 v155, vcc, 0, v155, vcc
	v_pk_mul_f32 v[88:89], v[88:89], v[182:183]
	v_pk_add_f32 v[158:159], v[158:159], 1.0 op_sel_hi:[1,0]
	global_load_dwordx4 v[132:135], v[136:137], off offset:-4096
	s_nop 0
	global_load_dwordx4 v[136:139], v[136:137], off
	v_pk_mul_f32 v[158:159], v[158:159], v[160:161]
	global_load_dwordx2 v[182:183], v[154:155], off offset:1024
	v_mad_i64_i32 v[154:155], vcc, v175, s2, v[2:3]
	v_lshl_add_u64 v[154:155], s[30:31], 0, v[154:155]
	v_pk_mul_f32 v[24:25], v[24:25], v[158:159]
	v_add_co_u32_e32 v158, vcc, s76, v154
	v_pk_mul_f32 v[8:9], v[8:9], v[152:153]
	s_nop 0
	v_addc_co_u32_e32 v159, vcc, 0, v155, vcc
	v_add_co_u32_e32 v154, vcc, s77, v154
	v_pk_add_f32 v[170:171], v[170:171], 1.0 op_sel_hi:[1,0]
	s_nop 0
	v_addc_co_u32_e32 v155, vcc, 0, v155, vcc
	global_load_dwordx2 v[174:175], v[158:159], off offset:3072
	global_load_dwordx2 v[184:185], v[154:155], off offset:1024
	global_load_dwordx2 v[186:187], v[156:157], off offset:3072
	v_mad_i64_i32 v[152:153], vcc, v176, s2, v[2:3]
	v_lshl_add_u64 v[152:153], s[30:31], 0, v[152:153]
	v_add_co_u32_e32 v154, vcc, s76, v152
	v_pk_add_f32 v[166:167], v[166:167], 1.0 op_sel_hi:[1,0]
	s_nop 0
	v_addc_co_u32_e32 v155, vcc, 0, v153, vcc
	v_add_co_u32_e32 v152, vcc, s77, v152
	v_pk_mul_f32 v[170:171], v[170:171], v[172:173]
	s_nop 0
	v_addc_co_u32_e32 v153, vcc, 0, v153, vcc
	v_mad_i64_i32 v[156:157], vcc, v177, s2, v[2:3]
	v_lshl_add_u64 v[156:157], s[30:31], 0, v[156:157]
	v_add_co_u32_e32 v158, vcc, s76, v156
	v_pk_mul_f32 v[166:167], v[166:167], v[168:169]
	s_nop 0
	v_addc_co_u32_e32 v159, vcc, 0, v157, vcc
	v_add_co_u32_e32 v156, vcc, s77, v156
	v_pk_mul_f32 v[72:73], v[72:73], v[170:171]
	v_pk_mul_f32 v[56:57], v[56:57], v[166:167]
	v_addc_co_u32_e32 v157, vcc, 0, v157, vcc
	global_load_dwordx2 v[170:171], v[154:155], off offset:3072
	global_load_dwordx2 v[172:173], v[152:153], off offset:1024
	global_load_dwordx2 v[166:167], v[158:159], off offset:3072
	global_load_dwordx2 v[168:169], v[156:157], off offset:1024
	v_mad_i64_i32 v[152:153], vcc, v178, s2, v[2:3]
	v_lshl_add_u64 v[152:153], s[30:31], 0, v[152:153]
	v_add_co_u32_e32 v154, vcc, s76, v152
	v_pk_add_f32 v[162:163], v[162:163], 1.0 op_sel_hi:[1,0]
	s_nop 0
	v_addc_co_u32_e32 v155, vcc, 0, v153, vcc
	v_add_co_u32_e32 v152, vcc, s77, v152
	v_pk_mul_f32 v[162:163], v[162:163], v[164:165]
	s_nop 0
	v_addc_co_u32_e32 v153, vcc, 0, v153, vcc
	v_mad_i64_i32 v[156:157], vcc, v179, s2, v[2:3]
	v_lshl_add_u64 v[156:157], s[30:31], 0, v[156:157]
	v_add_co_u32_e32 v158, vcc, s76, v156
	v_pk_mul_f32 v[40:41], v[40:41], v[162:163]
	s_nop 0
	v_addc_co_u32_e32 v159, vcc, 0, v157, vcc
	v_add_co_u32_e32 v156, vcc, s77, v156
	v_pk_mul_f32 v[120:121], v[120:121], v[190:191]
	s_nop 0
	v_addc_co_u32_e32 v157, vcc, 0, v157, vcc
	global_load_dwordx2 v[162:163], v[154:155], off offset:3072
	global_load_dwordx2 v[164:165], v[152:153], off offset:1024
	s_nop 0
	global_load_dwordx2 v[158:159], v[158:159], off offset:3072
	s_nop 0
	global_load_dwordx2 v[160:161], v[156:157], off offset:1024
	v_mad_i64_i32 v[152:153], vcc, v180, s2, v[2:3]
	v_lshl_add_u64 v[152:153], s[30:31], 0, v[152:153]
	v_add_co_u32_e32 v154, vcc, s76, v152
	s_waitcnt vmcnt(11)
	v_lshlrev_b32_e32 v0, 16, v182
	v_addc_co_u32_e32 v155, vcc, 0, v153, vcc
	v_add_co_u32_e32 v152, vcc, s77, v152
	v_add_f32_e32 v0, v136, v0
	s_nop 0
	v_addc_co_u32_e32 v153, vcc, 0, v153, vcc
	v_mad_i64_i32 v[2:3], vcc, v181, s2, v[2:3]
	v_lshl_add_u64 v[2:3], s[30:31], 0, v[2:3]
	v_add_co_u32_e32 v176, vcc, s76, v2
	v_mul_f32_e32 v0, 0xbfb8aa3b, v0
	s_nop 0
	v_addc_co_u32_e32 v177, vcc, 0, v3, vcc
	v_add_co_u32_e32 v178, vcc, s77, v2
	s_waitcnt vmcnt(8)
	v_lshlrev_b32_e32 v2, 16, v186
	v_add_f32_e32 v2, v132, v2
	v_mul_f32_e32 v2, 0xbfb8aa3b, v2
	v_exp_f32_e32 v0, v0
	v_exp_f32_e32 v140, v2
	v_and_b32_e32 v141, 0xffff0000, v186
	v_add_f32_e32 v141, v133, v141
	v_addc_co_u32_e32 v179, vcc, 0, v3, vcc
	global_load_dwordx2 v[154:155], v[154:155], off offset:3072
	s_nop 0
	global_load_dwordx2 v[156:157], v[152:153], off offset:1024
	global_load_dwordx2 v[2:3], v[176:177], off offset:3072
	s_nop 0
	global_load_dwordx2 v[152:153], v[178:179], off offset:1024
	v_min_f32_e32 v176, 0x60ad78ec, v0
	v_min_f32_e32 v0, 0x60ad78ec, v140
	v_and_b32_e32 v140, 0xffff0000, v182
	v_mul_f32_e32 v141, 0xbfb8aa3b, v141
	v_add_f32_e32 v140, v137, v140
	v_exp_f32_e32 v141, v141
	v_mul_f32_e32 v140, 0xbfb8aa3b, v140
	v_exp_f32_e32 v140, v140
	v_add_f32_e32 v0, 1.0, v0
	v_rcp_f32_e32 v178, v0
	v_min_f32_e32 v0, 0x60ad78ec, v141
	v_lshlrev_b32_e32 v141, 16, v187
	v_add_f32_e32 v141, v134, v141
	v_min_f32_e32 v177, 0x60ad78ec, v140
	v_lshlrev_b32_e32 v140, 16, v183
	v_mul_f32_e32 v141, 0xbfb8aa3b, v141
	v_add_f32_e32 v140, v138, v140
	v_exp_f32_e32 v141, v141
	v_mul_f32_e32 v140, 0xbfb8aa3b, v140
	v_exp_f32_e32 v140, v140
	v_add_f32_e32 v0, 1.0, v0
	v_rcp_f32_e32 v179, v0
	v_min_f32_e32 v0, 0x60ad78ec, v141
	v_and_b32_e32 v141, 0xffff0000, v187
	v_add_f32_e32 v141, v135, v141
	v_min_f32_e32 v180, 0x60ad78ec, v140
	v_and_b32_e32 v140, 0xffff0000, v183
	v_mul_f32_e32 v141, 0xbfb8aa3b, v141
	v_add_f32_e32 v140, v139, v140
	v_exp_f32_e32 v141, v141
	v_mul_f32_e32 v140, 0xbfb8aa3b, v140
	v_exp_f32_e32 v140, v140
	v_add_f32_e32 v0, 1.0, v0
	v_rcp_f32_e32 v182, v0
	v_min_f32_e32 v0, 0x60ad78ec, v141
	v_add_f32_e32 v0, 1.0, v0
	v_min_f32_e32 v181, 0x60ad78ec, v140
	v_rcp_f32_e32 v183, v0
	v_lshlrev_b32_e32 v0, 16, v184
	v_lshlrev_b32_e32 v140, 16, v174
	v_add_f32_e32 v0, v136, v0
	v_add_f32_e32 v140, v132, v140
	v_mul_f32_e32 v0, 0xbfb8aa3b, v0
	v_mul_f32_e32 v140, 0xbfb8aa3b, v140
	v_exp_f32_e32 v0, v0
	v_exp_f32_e32 v140, v140
	v_pk_add_f32 v[176:177], v[176:177], 1.0 op_sel_hi:[1,0]
	v_and_b32_e32 v141, 0xffff0000, v174
	v_pk_mul_f32 v[176:177], v[176:177], v[178:179]
	v_add_f32_e32 v141, v133, v141
	v_pk_mul_f32 v[116:117], v[116:117], v[176:177]
	v_min_f32_e32 v176, 0x60ad78ec, v0
	v_min_f32_e32 v0, 0x60ad78ec, v140
	v_and_b32_e32 v140, 0xffff0000, v184
	v_mul_f32_e32 v141, 0xbfb8aa3b, v141
	v_add_f32_e32 v140, v137, v140
	v_exp_f32_e32 v141, v141
	v_mul_f32_e32 v140, 0xbfb8aa3b, v140
	v_pk_add_f32 v[180:181], v[180:181], 1.0 op_sel_hi:[1,0]
	v_exp_f32_e32 v140, v140
	v_pk_mul_f32 v[178:179], v[180:181], v[182:183]
	v_add_f32_e32 v0, 1.0, v0
	v_pk_mul_f32 v[118:119], v[118:119], v[178:179]
	v_rcp_f32_e32 v178, v0
	v_min_f32_e32 v0, 0x60ad78ec, v141
	v_lshlrev_b32_e32 v141, 16, v175
	v_add_f32_e32 v141, v134, v141
	v_min_f32_e32 v177, 0x60ad78ec, v140
	v_lshlrev_b32_e32 v140, 16, v185
	v_mul_f32_e32 v141, 0xbfb8aa3b, v141
	v_add_f32_e32 v140, v138, v140
	v_exp_f32_e32 v141, v141
	v_mul_f32_e32 v140, 0xbfb8aa3b, v140
	v_exp_f32_e32 v140, v140
	v_add_f32_e32 v0, 1.0, v0
	v_rcp_f32_e32 v179, v0
	v_min_f32_e32 v0, 0x60ad78ec, v141
	v_and_b32_e32 v141, 0xffff0000, v175
	v_add_f32_e32 v141, v135, v141
	v_min_f32_e32 v174, 0x60ad78ec, v140
	v_and_b32_e32 v140, 0xffff0000, v185
	v_mul_f32_e32 v141, 0xbfb8aa3b, v141
	v_add_f32_e32 v140, v139, v140
	v_exp_f32_e32 v141, v141
	v_mul_f32_e32 v140, 0xbfb8aa3b, v140
	v_exp_f32_e32 v140, v140
	v_add_f32_e32 v0, 1.0, v0
	v_rcp_f32_e32 v180, v0
	v_min_f32_e32 v0, 0x60ad78ec, v141
	v_add_f32_e32 v0, 1.0, v0
	v_min_f32_e32 v175, 0x60ad78ec, v140
	v_rcp_f32_e32 v181, v0
	s_waitcnt vmcnt(10)
	v_lshlrev_b32_e32 v0, 16, v172
	v_lshlrev_b32_e32 v140, 16, v170
	v_add_f32_e32 v0, v136, v0
	v_add_f32_e32 v140, v132, v140
	v_mul_f32_e32 v0, 0xbfb8aa3b, v0
	v_mul_f32_e32 v140, 0xbfb8aa3b, v140
	v_exp_f32_e32 v0, v0
	v_exp_f32_e32 v140, v140
	v_pk_add_f32 v[174:175], v[174:175], 1.0 op_sel_hi:[1,0]
	v_and_b32_e32 v141, 0xffff0000, v170
	v_pk_mul_f32 v[174:175], v[174:175], v[180:181]
	v_add_f32_e32 v141, v133, v141
	v_pk_mul_f32 v[102:103], v[102:103], v[174:175]
	v_min_f32_e32 v174, 0x60ad78ec, v0
	v_min_f32_e32 v0, 0x60ad78ec, v140
	v_and_b32_e32 v140, 0xffff0000, v172
	v_mul_f32_e32 v141, 0xbfb8aa3b, v141
	v_add_f32_e32 v140, v137, v140
	v_exp_f32_e32 v141, v141
	v_mul_f32_e32 v140, 0xbfb8aa3b, v140
	v_pk_add_f32 v[176:177], v[176:177], 1.0 op_sel_hi:[1,0]
	v_exp_f32_e32 v140, v140
	v_pk_mul_f32 v[176:177], v[176:177], v[178:179]
	v_add_f32_e32 v0, 1.0, v0
	v_pk_mul_f32 v[100:101], v[100:101], v[176:177]
	v_rcp_f32_e32 v176, v0
	v_min_f32_e32 v0, 0x60ad78ec, v141
	v_lshlrev_b32_e32 v141, 16, v171
	v_add_f32_e32 v141, v134, v141
	v_min_f32_e32 v175, 0x60ad78ec, v140
	v_lshlrev_b32_e32 v140, 16, v173
	v_mul_f32_e32 v141, 0xbfb8aa3b, v141
	v_add_f32_e32 v140, v138, v140
	v_exp_f32_e32 v141, v141
	v_mul_f32_e32 v140, 0xbfb8aa3b, v140
	v_exp_f32_e32 v140, v140
	v_add_f32_e32 v0, 1.0, v0
	v_rcp_f32_e32 v177, v0
	v_min_f32_e32 v0, 0x60ad78ec, v141
	v_and_b32_e32 v141, 0xffff0000, v171
	v_add_f32_e32 v141, v135, v141
	v_min_f32_e32 v170, 0x60ad78ec, v140
	v_and_b32_e32 v140, 0xffff0000, v173
	v_mul_f32_e32 v141, 0xbfb8aa3b, v141
	v_add_f32_e32 v140, v139, v140
	v_exp_f32_e32 v141, v141
	v_mul_f32_e32 v140, 0xbfb8aa3b, v140
	v_exp_f32_e32 v140, v140
	v_add_f32_e32 v0, 1.0, v0
	v_rcp_f32_e32 v172, v0
	v_min_f32_e32 v0, 0x60ad78ec, v141
	v_add_f32_e32 v0, 1.0, v0
	v_min_f32_e32 v171, 0x60ad78ec, v140
	v_rcp_f32_e32 v173, v0
	s_waitcnt vmcnt(8)
	v_lshlrev_b32_e32 v0, 16, v168
	v_lshlrev_b32_e32 v140, 16, v166
	v_add_f32_e32 v0, v136, v0
	v_add_f32_e32 v140, v132, v140
	v_mul_f32_e32 v0, 0xbfb8aa3b, v0
	v_mul_f32_e32 v140, 0xbfb8aa3b, v140
	v_exp_f32_e32 v0, v0
	v_exp_f32_e32 v140, v140
	v_pk_add_f32 v[170:171], v[170:171], 1.0 op_sel_hi:[1,0]
	v_and_b32_e32 v141, 0xffff0000, v166
	v_pk_mul_f32 v[170:171], v[170:171], v[172:173]
	v_add_f32_e32 v141, v133, v141
	v_pk_mul_f32 v[86:87], v[86:87], v[170:171]
	v_min_f32_e32 v170, 0x60ad78ec, v0
	v_min_f32_e32 v0, 0x60ad78ec, v140
	v_and_b32_e32 v140, 0xffff0000, v168
	v_mul_f32_e32 v141, 0xbfb8aa3b, v141
	v_add_f32_e32 v140, v137, v140
	v_exp_f32_e32 v141, v141
	v_mul_f32_e32 v140, 0xbfb8aa3b, v140
	v_exp_f32_e32 v140, v140
	v_add_f32_e32 v0, 1.0, v0
	v_rcp_f32_e32 v172, v0
	v_min_f32_e32 v0, 0x60ad78ec, v141
	v_lshlrev_b32_e32 v141, 16, v167
	v_add_f32_e32 v141, v134, v141
	v_min_f32_e32 v171, 0x60ad78ec, v140
	v_lshlrev_b32_e32 v140, 16, v169
	v_mul_f32_e32 v141, 0xbfb8aa3b, v141
	v_add_f32_e32 v140, v138, v140
	v_exp_f32_e32 v141, v141
	v_mul_f32_e32 v140, 0xbfb8aa3b, v140
	v_exp_f32_e32 v140, v140
	v_add_f32_e32 v0, 1.0, v0
	v_rcp_f32_e32 v173, v0
	v_min_f32_e32 v0, 0x60ad78ec, v141
	v_and_b32_e32 v141, 0xffff0000, v167
	v_add_f32_e32 v141, v135, v141
	v_min_f32_e32 v166, 0x60ad78ec, v140
	v_and_b32_e32 v140, 0xffff0000, v169
	v_mul_f32_e32 v141, 0xbfb8aa3b, v141
	v_add_f32_e32 v140, v139, v140
	v_exp_f32_e32 v141, v141
	v_mul_f32_e32 v140, 0xbfb8aa3b, v140
	v_exp_f32_e32 v140, v140
	v_add_f32_e32 v0, 1.0, v0
	v_rcp_f32_e32 v168, v0
	v_min_f32_e32 v0, 0x60ad78ec, v141
	v_add_f32_e32 v0, 1.0, v0
	v_min_f32_e32 v167, 0x60ad78ec, v140
	v_rcp_f32_e32 v169, v0
	s_waitcnt vmcnt(6)
	v_lshlrev_b32_e32 v0, 16, v164
	v_lshlrev_b32_e32 v140, 16, v162
	v_add_f32_e32 v0, v136, v0
	v_add_f32_e32 v140, v132, v140
	v_mul_f32_e32 v0, 0xbfb8aa3b, v0
	v_mul_f32_e32 v140, 0xbfb8aa3b, v140
	v_exp_f32_e32 v0, v0
	v_exp_f32_e32 v140, v140
	v_pk_add_f32 v[166:167], v[166:167], 1.0 op_sel_hi:[1,0]
	v_and_b32_e32 v141, 0xffff0000, v162
	v_pk_mul_f32 v[166:167], v[166:167], v[168:169]
	v_add_f32_e32 v141, v133, v141
	v_pk_mul_f32 v[70:71], v[70:71], v[166:167]
	v_min_f32_e32 v166, 0x60ad78ec, v0
	v_min_f32_e32 v0, 0x60ad78ec, v140
	v_and_b32_e32 v140, 0xffff0000, v164
	v_mul_f32_e32 v141, 0xbfb8aa3b, v141
	v_add_f32_e32 v140, v137, v140
	v_exp_f32_e32 v141, v141
	v_mul_f32_e32 v140, 0xbfb8aa3b, v140
	v_exp_f32_e32 v140, v140
	v_add_f32_e32 v0, 1.0, v0
	v_rcp_f32_e32 v168, v0
	v_min_f32_e32 v0, 0x60ad78ec, v141
	v_lshlrev_b32_e32 v141, 16, v163
	v_add_f32_e32 v141, v134, v141
	v_min_f32_e32 v167, 0x60ad78ec, v140
	v_lshlrev_b32_e32 v140, 16, v165
	v_mul_f32_e32 v141, 0xbfb8aa3b, v141
	v_add_f32_e32 v140, v138, v140
	v_exp_f32_e32 v141, v141
	v_mul_f32_e32 v140, 0xbfb8aa3b, v140
	v_exp_f32_e32 v140, v140
	v_add_f32_e32 v0, 1.0, v0
	v_rcp_f32_e32 v169, v0
	v_min_f32_e32 v0, 0x60ad78ec, v141
	v_and_b32_e32 v141, 0xffff0000, v163
	v_add_f32_e32 v141, v135, v141
	v_min_f32_e32 v162, 0x60ad78ec, v140
	v_and_b32_e32 v140, 0xffff0000, v165
	v_mul_f32_e32 v141, 0xbfb8aa3b, v141
	v_add_f32_e32 v140, v139, v140
	v_exp_f32_e32 v141, v141
	v_mul_f32_e32 v140, 0xbfb8aa3b, v140
	v_exp_f32_e32 v140, v140
	v_add_f32_e32 v0, 1.0, v0
	v_rcp_f32_e32 v164, v0
	v_min_f32_e32 v0, 0x60ad78ec, v141
	v_add_f32_e32 v0, 1.0, v0
	v_min_f32_e32 v163, 0x60ad78ec, v140
	v_rcp_f32_e32 v165, v0
	s_waitcnt vmcnt(4)
	v_lshlrev_b32_e32 v0, 16, v160
	v_lshlrev_b32_e32 v140, 16, v158
	v_add_f32_e32 v0, v136, v0
	v_add_f32_e32 v140, v132, v140
	v_mul_f32_e32 v0, 0xbfb8aa3b, v0
	v_mul_f32_e32 v140, 0xbfb8aa3b, v140
	v_exp_f32_e32 v0, v0
	v_exp_f32_e32 v140, v140
	v_pk_add_f32 v[162:163], v[162:163], 1.0 op_sel_hi:[1,0]
	v_and_b32_e32 v141, 0xffff0000, v158
	v_pk_mul_f32 v[162:163], v[162:163], v[164:165]
	v_add_f32_e32 v141, v133, v141
	v_pk_mul_f32 v[54:55], v[54:55], v[162:163]
	v_min_f32_e32 v162, 0x60ad78ec, v0
	v_min_f32_e32 v0, 0x60ad78ec, v140
	v_and_b32_e32 v140, 0xffff0000, v160
	v_mul_f32_e32 v141, 0xbfb8aa3b, v141
	v_add_f32_e32 v140, v137, v140
	v_exp_f32_e32 v141, v141
	v_mul_f32_e32 v140, 0xbfb8aa3b, v140
	v_exp_f32_e32 v140, v140
	v_add_f32_e32 v0, 1.0, v0
	v_rcp_f32_e32 v164, v0
	v_min_f32_e32 v0, 0x60ad78ec, v141
	v_lshlrev_b32_e32 v141, 16, v159
	v_add_f32_e32 v141, v134, v141
	v_min_f32_e32 v163, 0x60ad78ec, v140
	v_lshlrev_b32_e32 v140, 16, v161
	v_mul_f32_e32 v141, 0xbfb8aa3b, v141
	v_add_f32_e32 v140, v138, v140
	v_exp_f32_e32 v141, v141
	v_mul_f32_e32 v140, 0xbfb8aa3b, v140
	v_exp_f32_e32 v140, v140
	v_add_f32_e32 v0, 1.0, v0
	v_rcp_f32_e32 v165, v0
	v_min_f32_e32 v0, 0x60ad78ec, v141
	v_and_b32_e32 v141, 0xffff0000, v159
	v_add_f32_e32 v141, v135, v141
	v_min_f32_e32 v158, 0x60ad78ec, v140
	v_and_b32_e32 v140, 0xffff0000, v161
	v_mul_f32_e32 v141, 0xbfb8aa3b, v141
	v_add_f32_e32 v140, v139, v140
	v_exp_f32_e32 v141, v141
	v_mul_f32_e32 v140, 0xbfb8aa3b, v140
	v_exp_f32_e32 v140, v140
	v_add_f32_e32 v0, 1.0, v0
	v_rcp_f32_e32 v160, v0
	v_min_f32_e32 v0, 0x60ad78ec, v141
	v_add_f32_e32 v0, 1.0, v0
	v_min_f32_e32 v159, 0x60ad78ec, v140
	v_rcp_f32_e32 v161, v0
	s_waitcnt vmcnt(2)
	v_lshlrev_b32_e32 v0, 16, v156
	v_lshlrev_b32_e32 v140, 16, v154
	v_add_f32_e32 v0, v136, v0
	v_add_f32_e32 v140, v132, v140
	v_mul_f32_e32 v0, 0xbfb8aa3b, v0
	v_mul_f32_e32 v140, 0xbfb8aa3b, v140
	v_and_b32_e32 v141, 0xffff0000, v154
	v_exp_f32_e32 v0, v0
	v_exp_f32_e32 v140, v140
	v_add_f32_e32 v141, v133, v141
	v_mul_f32_e32 v141, 0xbfb8aa3b, v141
	v_pk_add_f32 v[158:159], v[158:159], 1.0 op_sel_hi:[1,0]
	v_exp_f32_e32 v141, v141
	v_pk_mul_f32 v[158:159], v[158:159], v[160:161]
	v_pk_add_f32 v[174:175], v[174:175], 1.0 op_sel_hi:[1,0]
	v_pk_mul_f32 v[38:39], v[38:39], v[158:159]
	v_min_f32_e32 v158, 0x60ad78ec, v0
	v_min_f32_e32 v0, 0x60ad78ec, v140
	v_add_f32_e32 v0, 1.0, v0
	v_rcp_f32_e32 v160, v0
	v_min_f32_e32 v0, 0x60ad78ec, v141
	v_lshlrev_b32_e32 v141, 16, v155
	v_add_f32_e32 v141, v134, v141
	v_and_b32_e32 v140, 0xffff0000, v156
	v_mul_f32_e32 v141, 0xbfb8aa3b, v141
	v_add_f32_e32 v140, v137, v140
	v_exp_f32_e32 v141, v141
	v_mul_f32_e32 v140, 0xbfb8aa3b, v140
	v_exp_f32_e32 v140, v140
	v_add_f32_e32 v0, 1.0, v0
	v_rcp_f32_e32 v161, v0
	v_min_f32_e32 v0, 0x60ad78ec, v141
	v_and_b32_e32 v141, 0xffff0000, v155
	v_add_f32_e32 v141, v135, v141
	v_min_f32_e32 v159, 0x60ad78ec, v140
	v_lshlrev_b32_e32 v140, 16, v157
	v_mul_f32_e32 v141, 0xbfb8aa3b, v141
	v_add_f32_e32 v140, v138, v140
	v_exp_f32_e32 v141, v141
	v_mul_f32_e32 v140, 0xbfb8aa3b, v140
	v_exp_f32_e32 v140, v140
	v_add_f32_e32 v0, 1.0, v0
	v_rcp_f32_e32 v156, v0
	v_min_f32_e32 v0, 0x60ad78ec, v141
	v_add_f32_e32 v0, 1.0, v0
	v_min_f32_e32 v154, 0x60ad78ec, v140
	v_and_b32_e32 v140, 0xffff0000, v157
	v_rcp_f32_e32 v157, v0
	s_waitcnt vmcnt(0)
	v_lshlrev_b32_e32 v0, 16, v152
	v_add_f32_e32 v0, v136, v0
	v_lshlrev_b32_e32 v136, 16, v2
	v_add_f32_e32 v132, v132, v136
	v_mul_f32_e32 v0, 0xbfb8aa3b, v0
	v_mul_f32_e32 v132, 0xbfb8aa3b, v132
	v_exp_f32_e32 v0, v0
	v_exp_f32_e32 v136, v132
	v_and_b32_e32 v2, 0xffff0000, v2
	v_add_f32_e32 v2, v133, v2
	v_min_f32_e32 v132, 0x60ad78ec, v0
	v_min_f32_e32 v0, 0x60ad78ec, v136
	v_and_b32_e32 v136, 0xffff0000, v152
	v_add_f32_e32 v136, v137, v136
	v_mul_f32_e32 v136, 0xbfb8aa3b, v136
	v_exp_f32_e32 v137, v136
	v_mul_f32_e32 v2, 0xbfb8aa3b, v2
	v_exp_f32_e32 v2, v2
	v_add_f32_e32 v0, 1.0, v0
	v_min_f32_e32 v133, 0x60ad78ec, v137
	v_lshlrev_b32_e32 v137, 16, v3
	v_add_f32_e32 v134, v134, v137
	v_mul_f32_e32 v134, 0xbfb8aa3b, v134
	v_exp_f32_e32 v134, v134
	v_and_b32_e32 v3, 0xffff0000, v3
	v_add_f32_e32 v3, v135, v3
	v_rcp_f32_e32 v136, v0
	v_min_f32_e32 v0, 0x60ad78ec, v2
	v_mul_f32_e32 v3, 0xbfb8aa3b, v3
	v_add_f32_e32 v0, 1.0, v0
	v_exp_f32_e32 v135, v3
	v_lshlrev_b32_e32 v2, 16, v153
	v_rcp_f32_e32 v137, v0
	v_min_f32_e32 v0, 0x60ad78ec, v134
	v_and_b32_e32 v134, 0xffff0000, v153
	v_add_f32_e32 v140, v139, v140
	v_add_f32_e32 v2, v138, v2
	v_add_f32_e32 v134, v139, v134
	v_mul_f32_e32 v140, 0xbfb8aa3b, v140
	v_mul_f32_e32 v2, 0xbfb8aa3b, v2
	v_mul_f32_e32 v134, 0xbfb8aa3b, v134
	v_add_f32_e32 v0, 1.0, v0
	v_exp_f32_e32 v140, v140
	v_exp_f32_e32 v2, v2
	v_exp_f32_e32 v138, v134
	v_rcp_f32_e32 v134, v0
	v_min_f32_e32 v0, 0x60ad78ec, v135
	v_add_f32_e32 v0, 1.0, v0
	v_rcp_f32_e32 v135, v0
	v_min_f32_e32 v155, 0x60ad78ec, v140
	v_min_f32_e32 v2, 0x60ad78ec, v2
	v_min_f32_e32 v3, 0x60ad78ec, v138
	v_pk_add_f32 v[170:171], v[170:171], 1.0 op_sel_hi:[1,0]
	v_pk_add_f32 v[166:167], v[166:167], 1.0 op_sel_hi:[1,0]
	v_pk_add_f32 v[162:163], v[162:163], 1.0 op_sel_hi:[1,0]
	v_pk_add_f32 v[154:155], v[154:155], 1.0 op_sel_hi:[1,0]
	v_pk_add_f32 v[158:159], v[158:159], 1.0 op_sel_hi:[1,0]
	v_pk_add_f32 v[2:3], v[2:3], 1.0 op_sel_hi:[1,0]
	v_pk_add_f32 v[132:133], v[132:133], 1.0 op_sel_hi:[1,0]
	v_pk_mul_f32 v[174:175], v[174:175], v[176:177]
	v_pk_mul_f32 v[170:171], v[170:171], v[172:173]
	v_pk_mul_f32 v[166:167], v[166:167], v[168:169]
	v_pk_mul_f32 v[162:163], v[162:163], v[164:165]
	v_pk_mul_f32 v[158:159], v[158:159], v[160:161]
	v_pk_mul_f32 v[154:155], v[154:155], v[156:157]
	v_pk_mul_f32 v[132:133], v[132:133], v[136:137]
	v_pk_mul_f32 v[2:3], v[2:3], v[134:135]
	v_pk_mul_f32 v[84:85], v[84:85], v[174:175]
	v_pk_mul_f32 v[68:69], v[68:69], v[170:171]
	v_pk_mul_f32 v[52:53], v[52:53], v[166:167]
	v_pk_mul_f32 v[36:37], v[36:37], v[162:163]
	v_pk_mul_f32 v[22:23], v[22:23], v[154:155]
	v_pk_mul_f32 v[20:21], v[20:21], v[158:159]
	v_pk_mul_f32 v[6:7], v[6:7], v[2:3]
	v_pk_mul_f32 v[4:5], v[4:5], v[132:133]
